# layer-0 residual x1 is no longer written to memory: the last phase recomputes it from x and the layer-0 Y (kept in the H region); layer-1 H moved to the YCAT region
# speedup vs baseline: 1.0087x; 1.0087x over previous
.LBB0_23:
	s_add_i32 s62, s92, -2
	s_ashr_i32 s64, s62, 2
	s_and_b32 s63, s62, 3
	s_cmp_lt_i32 s63, 2
	s_mov_b64 s[0:1], -1
	s_cbranch_scc1 .LBB0_58
	s_cmp_gt_i32 s63, 2
	s_cbranch_scc0 .LBB0_36
	s_cmp_gt_u32 s62, 3
	s_cbranch_scc0 .LBB0_30
	v_mov_b32_e32 v0, v186
	v_readlane_b32 s0, v255, 16
	v_ashrrev_i32_e32 v2, 6, v0
	v_add_u32_e32 v3, s48, v2
	v_ashrrev_i32_e32 v2, 31, v3
	v_xor_b32_e32 v18, s0, v2
	v_sub_u32_e32 v2, 0, v3
	v_max_i32_e32 v2, v3, v2
	v_mul_hi_u32 v4, v2, v187
	v_readlane_b32 s0, v255, 14
	s_nop 1
	v_mul_lo_u32 v5, v4, s0
	v_sub_u32_e32 v2, v2, v5
	v_add_u32_e32 v5, 1, v4
	v_cmp_le_u32_e32 vcc, s0, v2
	s_nop 1
	v_cndmask_b32_e32 v4, v4, v5, vcc
	v_subrev_u32_e32 v5, s0, v2
	v_cndmask_b32_e32 v2, v2, v5, vcc
	v_add_u32_e32 v5, 1, v4
	v_cmp_le_u32_e32 vcc, s0, v2
	s_movk_i32 s0, 0x400
	s_nop 0
	v_cndmask_b32_e32 v2, v4, v5, vcc
	v_xor_b32_e32 v19, v2, v18
	v_sub_u32_e32 v2, v19, v18
	v_mul_lo_u32 v4, v2, s31
	v_sub_u32_e32 v20, v3, v4
	v_cmp_gt_i32_e32 vcc, s0, v20
	s_and_saveexec_b64 s[18:19], vcc
	s_cbranch_execz .LBB0_29
	v_and_b32_e32 v21, 63, v0
	v_add_u32_e32 v0, 8, v2
	v_mov_b64_e32 v[2:3], s[90:91]
	v_mad_i64_i32 v[2:3], s[0:1], v0, s29, v[2:3]
	s_mov_b64 s[0:1], 0x1a02000
	s_nop 0
	v_lshl_add_u64 v[16:17], v[2:3], 0, s[0:1]
	v_mov_b64_e32 v[224:225], v[16:17]
	v_lshlrev_b32_e32 v0, 4, v21
	v_readlane_b32 s0, v253, 13
	v_lshl_add_u64 v[2:3], v[16:17], 0, v[0:1]
	v_readlane_b32 s1, v253, 14
	global_load_dwordx4 v[4:7], v[2:3], off
	s_waitcnt vmcnt(0)
	v_lshlrev_b32_e32 v120, 2, v20
	v_lshl_add_u64 v[82:83], s[88:89], 0, v[0:1]
	v_lshlrev_b32_e32 v18, 12, v18
	s_mov_b64 s[34:35], 0
	global_load_dwordx4 v[8:11], v0, s[0:1]
	s_waitcnt vmcnt(0)
	v_mul_f32_e32 v3, v7, v11
	v_mul_f32_e32 v2, v6, v10
	v_or_b32_e32 v6, 0x400, v0
	v_mov_b32_e32 v7, v1
	v_mul_f32_e32 v5, v5, v9
	v_mul_f32_e32 v4, v4, v8
	v_lshl_add_u64 v[8:9], v[16:17], 0, v[6:7]
	global_load_dwordx4 v[8:11], v[8:9], off
	s_nop 0
	global_load_dwordx4 v[12:15], v6, s[0:1]
	s_waitcnt vmcnt(0)
	v_mul_f32_e32 v7, v11, v15
	v_mul_f32_e32 v6, v10, v14
	v_or_b32_e32 v10, 0x800, v0
	v_mov_b32_e32 v11, v1
	v_mul_f32_e32 v9, v9, v13
	v_mul_f32_e32 v8, v8, v12
	v_lshl_add_u64 v[12:13], v[16:17], 0, v[10:11]
	global_load_dwordx4 v[12:15], v[12:13], off
	s_nop 0
	global_load_dwordx4 v[22:25], v10, s[0:1]
	s_waitcnt vmcnt(0)
	v_mul_f32_e32 v11, v15, v25
	v_mul_f32_e32 v10, v14, v24
	v_or_b32_e32 v14, 0xc00, v0
	v_mov_b32_e32 v15, v1
	v_lshl_add_u64 v[16:17], v[16:17], 0, v[14:15]
	v_mul_f32_e32 v13, v13, v23
	v_mul_f32_e32 v12, v12, v22
	global_load_dwordx4 v[22:25], v[16:17], off
	global_load_dwordx4 v[26:29], v14, s[0:1]
	v_lshlrev_b32_e32 v0, 3, v21
	v_lshl_add_u64 v[84:85], s[12:13], 0, v[0:1]
	v_lshl_add_u32 v0, v19, 12, v120
	v_or_b32_e32 v0, 3, v0
	v_sub_u32_e32 v86, v0, v18
	s_waitcnt vmcnt(0)
	v_mul_f32_e32 v15, v25, v29
	v_mul_f32_e32 v14, v24, v28
	v_mul_f32_e32 v17, v23, v27
	v_mul_f32_e32 v16, v22, v26
	v_lshlrev_b32_e32 v226, 4, v21
	v_mov_b32_e32 v227, 0
	v_add_co_u32_e32 v224, vcc, 0xfffe8000, v224
	v_addc_co_u32_e32 v225, vcc, -1, v225, vcc
	v_lshl_add_u64 v[224:225], v[224:225], 0, v[226:227]
	s_sub_u32 s0, s0, 0x1000
	s_subb_u32 s1, s1, 0
	global_load_dwordx4 v[208:211], v[224:225], off
	global_load_dwordx4 v[212:215], v[224:225], off offset:1024
	global_load_dwordx4 v[216:219], v[224:225], off offset:2048
	global_load_dwordx4 v[220:223], v[224:225], off offset:3072
	global_load_dwordx4 v[174:177], v226, s[0:1]
	global_load_dwordx4 v[178:181], v226, s[0:1] offset:1024
	global_load_dwordx4 v[182:185], v226, s[0:1] offset:2048
	global_load_dwordx4 v[246:249], v226, s[0:1] offset:3072
	v_readlane_b32 s66, v253, 15
	v_readlane_b32 s67, v253, 16
	v_readlane_b32 s0, v255, 8
	v_readlane_b32 s1, v255, 9
	s_sub_u32 s66, s66, s88
	s_subb_u32 s67, s67, s89
	v_lshrrev_b32_e32 v244, 1, v226
	v_mov_b32_e32 v245, 0
	v_lshl_add_u64 v[206:207], s[0:1], 0, v[244:245]
	s_waitcnt vmcnt(0)
	v_mul_f32_e32 v192, v208, v174
	v_mul_f32_e32 v193, v209, v175
	v_mul_f32_e32 v190, v210, v176
	v_mul_f32_e32 v191, v211, v177
	v_mul_f32_e32 v196, v212, v178
	v_mul_f32_e32 v197, v213, v179
	v_mul_f32_e32 v194, v214, v180
	v_mul_f32_e32 v195, v215, v181
	v_mul_f32_e32 v200, v216, v182
	v_mul_f32_e32 v201, v217, v183
	v_mul_f32_e32 v198, v218, v184
	v_mul_f32_e32 v199, v219, v185
	v_mul_f32_e32 v204, v220, v246
	v_mul_f32_e32 v205, v221, v247
	v_mul_f32_e32 v202, v222, v248
	v_mul_f32_e32 v203, v223, v249
.LBB0_28:
	v_add_u32_e32 v210, -3, v86
	v_ashrrev_i32_e32 v211, 31, v210
	v_lshlrev_b64 v[210:211], 11, v[210:211]
	v_lshl_add_u64 v[210:211], v[206:207], 0, v[210:211]
	global_load_dwordx2 v[142:143], v[210:211], off
	global_load_dwordx2 v[144:145], v[210:211], off offset:512
	global_load_dwordx2 v[146:147], v[210:211], off offset:1024
	global_load_dwordx2 v[148:149], v[210:211], off offset:1536
	v_add_u32_e32 v210, -2, v86
	v_ashrrev_i32_e32 v211, 31, v210
	v_lshlrev_b64 v[210:211], 11, v[210:211]
	v_lshl_add_u64 v[210:211], v[206:207], 0, v[210:211]
	global_load_dwordx2 v[150:151], v[210:211], off
	global_load_dwordx2 v[152:153], v[210:211], off offset:512
	global_load_dwordx2 v[154:155], v[210:211], off offset:1024
	global_load_dwordx2 v[156:157], v[210:211], off offset:1536
	v_add_u32_e32 v210, -1, v86
	v_ashrrev_i32_e32 v211, 31, v210
	v_lshlrev_b64 v[210:211], 11, v[210:211]
	v_lshl_add_u64 v[210:211], v[206:207], 0, v[210:211]
	global_load_dwordx2 v[158:159], v[210:211], off
	global_load_dwordx2 v[160:161], v[210:211], off offset:512
	global_load_dwordx2 v[162:163], v[210:211], off offset:1024
	global_load_dwordx2 v[164:165], v[210:211], off offset:1536
	v_add_u32_e32 v210, 0, v86
	v_ashrrev_i32_e32 v211, 31, v210
	v_lshlrev_b64 v[210:211], 11, v[210:211]
	v_lshl_add_u64 v[210:211], v[206:207], 0, v[210:211]
	global_load_dwordx2 v[166:167], v[210:211], off
	global_load_dwordx2 v[168:169], v[210:211], off offset:512
	global_load_dwordx2 v[170:171], v[210:211], off offset:1024
	global_load_dwordx2 v[172:173], v[210:211], off offset:1536
	v_add_u32_e32 v18, -3, v86
	v_ashrrev_i32_e32 v19, 31, v18
	v_lshlrev_b64 v[20:21], 12, v[18:19]
	v_lshl_add_u64 v[104:105], v[82:83], 0, v[20:21]
	v_lshlrev_b64 v[18:19], 11, v[18:19]
	v_lshl_add_u64 v[18:19], v[84:85], 0, v[18:19]
	v_lshl_add_u64 v[208:209], v[104:105], 0, s[66:67]
	global_load_dwordx4 v[78:81], v[208:209], off
	global_load_dwordx2 v[122:123], v[18:19], off
	global_load_dwordx4 v[74:77], v[208:209], off offset:1024
	global_load_dwordx2 v[124:125], v[18:19], off offset:512
	global_load_dwordx4 v[70:73], v[208:209], off offset:2048
	global_load_dwordx2 v[126:127], v[18:19], off offset:1024
	global_load_dwordx4 v[66:69], v[208:209], off offset:3072
	global_load_dwordx2 v[128:129], v[18:19], off offset:1536
	v_add_u32_e32 v18, -2, v86
	v_ashrrev_i32_e32 v19, 31, v18
	v_lshlrev_b64 v[20:21], 12, v[18:19]
	v_lshl_add_u64 v[94:95], v[82:83], 0, v[20:21]
	v_lshlrev_b64 v[18:19], 11, v[18:19]
	v_lshl_add_u64 v[18:19], v[84:85], 0, v[18:19]
	v_lshl_add_u64 v[208:209], v[94:95], 0, s[66:67]
	global_load_dwordx4 v[62:65], v[208:209], off
	global_load_dwordx2 v[118:119], v[18:19], off
	global_load_dwordx4 v[58:61], v[208:209], off offset:1024
	global_load_dwordx2 v[116:117], v[18:19], off offset:512
	global_load_dwordx4 v[54:57], v[208:209], off offset:2048
	global_load_dwordx2 v[114:115], v[18:19], off offset:1024
	global_load_dwordx4 v[50:53], v[208:209], off offset:3072
	global_load_dwordx2 v[112:113], v[18:19], off offset:1536
	v_add_u32_e32 v18, -1, v86
	v_ashrrev_i32_e32 v19, 31, v18
	v_lshlrev_b64 v[20:21], 12, v[18:19]
	v_lshlrev_b64 v[18:19], 11, v[18:19]
	v_lshl_add_u64 v[90:91], v[82:83], 0, v[20:21]
	v_lshl_add_u64 v[18:19], v[84:85], 0, v[18:19]
	v_ashrrev_i32_e32 v87, 31, v86
	v_lshl_add_u64 v[208:209], v[90:91], 0, s[66:67]
	global_load_dwordx4 v[46:49], v[208:209], off
	global_load_dwordx2 v[110:111], v[18:19], off
	global_load_dwordx4 v[42:45], v[208:209], off offset:1024
	global_load_dwordx2 v[108:109], v[18:19], off offset:512
	global_load_dwordx4 v[38:41], v[208:209], off offset:2048
	global_load_dwordx2 v[106:107], v[18:19], off offset:1024
	global_load_dwordx4 v[34:37], v[208:209], off offset:3072
	global_load_dwordx2 v[102:103], v[18:19], off offset:1536
	v_lshlrev_b64 v[18:19], 12, v[86:87]
	v_lshl_add_u64 v[88:89], v[82:83], 0, v[18:19]
	v_lshlrev_b64 v[18:19], 11, v[86:87]
	v_lshl_add_u64 v[92:93], v[84:85], 0, v[18:19]
	v_lshl_add_u64 v[208:209], v[88:89], 0, s[66:67]
	global_load_dwordx4 v[30:33], v[208:209], off
	global_load_dwordx2 v[100:101], v[92:93], off
	global_load_dwordx4 v[26:29], v[208:209], off offset:1024
	global_load_dwordx2 v[98:99], v[92:93], off offset:512
	global_load_dwordx4 v[22:25], v[208:209], off offset:2048
	global_load_dwordx2 v[96:97], v[92:93], off offset:1024
	global_load_dwordx4 v[18:21], v[208:209], off offset:3072
	s_nop 0
	global_load_dwordx2 v[92:93], v[92:93], off offset:1536
	v_add_u32_e32 v120, s3, v120
	v_add_u32_e32 v86, s3, v86
	s_waitcnt vmcnt(30)
	v_lshlrev_b32_e32 v0, 16, v142
	v_and_b32_e32 v87, 0xffff0000, v142
	v_and_b32_e32 v142, 0xffff0000, v143
	v_lshlrev_b32_e32 v121, 16, v143
	v_mul_f32_e32 v143, v87, v87
	v_mul_f32_e32 v130, v142, v142
	v_fmac_f32_e32 v143, v0, v0
	v_fmac_f32_e32 v130, v121, v121
	v_add_f32_e32 v143, v143, v130
	s_waitcnt vmcnt(28)
	v_lshlrev_b32_e32 v130, 16, v144
	v_and_b32_e32 v144, 0xffff0000, v144
	v_lshlrev_b32_e32 v131, 16, v145
	v_and_b32_e32 v145, 0xffff0000, v145
	v_mul_f32_e32 v132, v144, v144
	v_mul_f32_e32 v133, v145, v145
	v_fmac_f32_e32 v132, v130, v130
	v_fmac_f32_e32 v133, v131, v131
	v_add_f32_e32 v132, v132, v133
	v_add_f32_e32 v143, v143, v132
	s_waitcnt vmcnt(26)
	v_lshlrev_b32_e32 v132, 16, v146
	v_and_b32_e32 v146, 0xffff0000, v146
	v_lshlrev_b32_e32 v133, 16, v147
	v_and_b32_e32 v147, 0xffff0000, v147
	v_mul_f32_e32 v134, v146, v146
	v_mul_f32_e32 v135, v147, v147
	v_fmac_f32_e32 v134, v132, v132
	v_fmac_f32_e32 v135, v133, v133
	v_add_f32_e32 v134, v134, v135
	v_add_f32_e32 v143, v143, v134
	s_waitcnt vmcnt(24)
	v_lshlrev_b32_e32 v134, 16, v148
	v_and_b32_e32 v148, 0xffff0000, v148
	v_lshlrev_b32_e32 v135, 16, v149
	v_and_b32_e32 v149, 0xffff0000, v149
	v_mul_f32_e32 v136, v148, v148
	v_mul_f32_e32 v137, v149, v149
	v_fmac_f32_e32 v136, v134, v134
	v_fmac_f32_e32 v137, v135, v135
	v_add_f32_e32 v136, v136, v137
	v_add_f32_e32 v143, v143, v136
	s_nop 1
	v_add_f32_dpp v143, v143, v143 quad_perm:[1,0,3,2] row_mask:0xf bank_mask:0xf bound_ctrl:1
	s_nop 1
	v_add_f32_dpp v143, v143, v143 quad_perm:[2,3,0,1] row_mask:0xf bank_mask:0xf bound_ctrl:1
	s_nop 1
	v_add_f32_dpp v143, v143, v143 row_half_mirror row_mask:0xf bank_mask:0xf bound_ctrl:1
	s_nop 1
	v_add_f32_dpp v143, v143, v143 row_mirror row_mask:0xf bank_mask:0xf bound_ctrl:1
	s_nop 0
	v_readlane_b32 s1, v143, 16
	v_readlane_b32 s6, v143, 48
	v_readlane_b32 s0, v143, 0
	v_readlane_b32 s2, v143, 32
	v_mov_b32_e32 v143, s1
	v_mov_b32_e32 v136, s6
	v_add_f32_e32 v143, s0, v143
	v_add_f32_e32 v136, s2, v136
	v_add_f32_e32 v143, v143, v136
	v_fmamk_f32 v143, v143, 0x3a800000, v188
	v_cmp_gt_f32_e32 vcc, s49, v143
	v_mul_f32_e32 v136, 0x4f800000, v143
	s_nop 0
	v_cndmask_b32_e32 v143, v143, v136, vcc
	v_sqrt_f32_e32 v136, v143
	s_nop 0
	v_add_u32_e32 v137, -1, v136
	v_fma_f32 v138, -v137, v136, v143
	v_cmp_ge_f32_e64 s[0:1], 0, v138
	v_add_u32_e32 v138, 1, v136
	s_nop 0
	v_cndmask_b32_e64 v137, v136, v137, s[0:1]
	v_fma_f32 v136, -v138, v136, v143
	v_cmp_lt_f32_e64 s[0:1], 0, v136
	s_nop 1
	v_cndmask_b32_e64 v136, v137, v138, s[0:1]
	v_mul_f32_e32 v137, 0x37800000, v136
	v_cndmask_b32_e32 v136, v136, v137, vcc
	v_cmp_class_f32_e32 vcc, v143, v189
	s_nop 1
	v_cndmask_b32_e32 v143, v136, v143, vcc
	v_div_scale_f32 v136, s[0:1], v143, v143, 1.0
	v_rcp_f32_e32 v137, v136
	s_nop 0
	v_fma_f32 v138, -v136, v137, 1.0
	v_fmac_f32_e32 v137, v138, v137
	v_div_scale_f32 v138, vcc, 1.0, v143, 1.0
	v_mul_f32_e32 v139, v138, v137
	v_fma_f32 v140, -v136, v139, v138
	v_fmac_f32_e32 v139, v140, v137
	v_fma_f32 v136, -v136, v139, v138
	v_div_fmas_f32 v136, v136, v137, v139
	v_div_fixup_f32 v143, v136, v143, 1.0
	v_mul_f32_e32 v0, v0, v143
	v_mul_f32_e32 v87, v87, v143
	v_mul_f32_e32 v121, v121, v143
	v_mul_f32_e32 v142, v142, v143
	v_fma_f32 v81, v191, v142, v81
	v_fma_f32 v80, v190, v121, v80
	v_fma_f32 v79, v193, v87, v79
	v_fmac_f32_e32 v78, v192, v0
	v_mul_f32_e32 v0, v130, v143
	v_fmac_f32_e32 v74, v196, v0
	v_mul_f32_e32 v212, v144, v143
	v_mul_f32_e32 v213, v131, v143
	v_mul_f32_e32 v214, v145, v143
	v_fma_f32 v77, v195, v214, v77
	v_fma_f32 v76, v194, v213, v76
	v_fma_f32 v75, v197, v212, v75
	v_mul_f32_e32 v0, v132, v143
	v_fmac_f32_e32 v70, v200, v0
	v_mul_f32_e32 v216, v146, v143
	v_mul_f32_e32 v217, v133, v143
	v_mul_f32_e32 v218, v147, v143
	v_fma_f32 v73, v199, v218, v73
	v_fma_f32 v72, v198, v217, v72
	v_fma_f32 v71, v201, v216, v71
	v_mul_f32_e32 v0, v134, v143
	v_fmac_f32_e32 v66, v204, v0
	v_mul_f32_e32 v220, v148, v143
	v_mul_f32_e32 v221, v135, v143
	v_mul_f32_e32 v222, v149, v143
	v_fma_f32 v69, v203, v222, v69
	v_fma_f32 v68, v202, v221, v68
	v_fma_f32 v67, v205, v220, v67
	s_waitcnt vmcnt(30)
	v_lshlrev_b32_e32 v0, 16, v122
	v_and_b32_e32 v87, 0xffff0000, v122
	v_and_b32_e32 v122, 0xffff0000, v123
	v_lshlrev_b32_e32 v121, 16, v123
	v_mul_f32_e32 v123, v87, v87
	v_mul_f32_e32 v130, v122, v122
	v_fmac_f32_e32 v123, v0, v0
	v_fmac_f32_e32 v130, v121, v121
	v_add_f32_e32 v123, v123, v130
	s_waitcnt vmcnt(28)
	v_lshlrev_b32_e32 v130, 16, v124
	v_and_b32_e32 v124, 0xffff0000, v124
	v_lshlrev_b32_e32 v131, 16, v125
	v_and_b32_e32 v125, 0xffff0000, v125
	v_mul_f32_e32 v132, v124, v124
	v_mul_f32_e32 v133, v125, v125
	v_fmac_f32_e32 v132, v130, v130
	v_fmac_f32_e32 v133, v131, v131
	v_add_f32_e32 v132, v132, v133
	v_add_f32_e32 v123, v123, v132
	s_waitcnt vmcnt(26)
	v_lshlrev_b32_e32 v132, 16, v126
	v_and_b32_e32 v126, 0xffff0000, v126
	v_lshlrev_b32_e32 v133, 16, v127
	v_and_b32_e32 v127, 0xffff0000, v127
	v_mul_f32_e32 v134, v126, v126
	v_mul_f32_e32 v135, v127, v127
	v_fmac_f32_e32 v134, v132, v132
	v_fmac_f32_e32 v135, v133, v133
	v_add_f32_e32 v134, v134, v135
	v_add_f32_e32 v123, v123, v134
	s_waitcnt vmcnt(24)
	v_lshlrev_b32_e32 v134, 16, v128
	v_and_b32_e32 v128, 0xffff0000, v128
	v_lshlrev_b32_e32 v135, 16, v129
	v_and_b32_e32 v129, 0xffff0000, v129
	v_mul_f32_e32 v136, v128, v128
	v_mul_f32_e32 v137, v129, v129
	v_fmac_f32_e32 v136, v134, v134
	v_fmac_f32_e32 v137, v135, v135
	v_add_f32_e32 v136, v136, v137
	v_add_f32_e32 v123, v123, v136
	s_nop 1
	v_add_f32_dpp v123, v123, v123 quad_perm:[1,0,3,2] row_mask:0xf bank_mask:0xf bound_ctrl:1
	s_nop 1
	v_add_f32_dpp v123, v123, v123 quad_perm:[2,3,0,1] row_mask:0xf bank_mask:0xf bound_ctrl:1
	s_nop 1
	v_add_f32_dpp v123, v123, v123 row_half_mirror row_mask:0xf bank_mask:0xf bound_ctrl:1
	s_nop 1
	v_add_f32_dpp v123, v123, v123 row_mirror row_mask:0xf bank_mask:0xf bound_ctrl:1
	s_nop 0
	v_readlane_b32 s1, v123, 16
	v_readlane_b32 s6, v123, 48
	v_readlane_b32 s0, v123, 0
	v_readlane_b32 s2, v123, 32
	v_mov_b32_e32 v123, s1
	v_mov_b32_e32 v136, s6
	v_add_f32_e32 v123, s0, v123
	v_add_f32_e32 v136, s2, v136
	v_add_f32_e32 v123, v123, v136
	v_fmamk_f32 v123, v123, 0x3a800000, v188
	v_cmp_gt_f32_e32 vcc, s49, v123
	v_mul_f32_e32 v136, 0x4f800000, v123
	s_nop 0
	v_cndmask_b32_e32 v123, v123, v136, vcc
	v_sqrt_f32_e32 v136, v123
	s_nop 0
	v_add_u32_e32 v137, -1, v136
	v_fma_f32 v138, -v137, v136, v123
	v_cmp_ge_f32_e64 s[0:1], 0, v138
	v_add_u32_e32 v138, 1, v136
	s_nop 0
	v_cndmask_b32_e64 v137, v136, v137, s[0:1]
	v_fma_f32 v136, -v138, v136, v123
	v_cmp_lt_f32_e64 s[0:1], 0, v136
	s_nop 1
	v_cndmask_b32_e64 v136, v137, v138, s[0:1]
	v_mul_f32_e32 v137, 0x37800000, v136
	v_cndmask_b32_e32 v136, v136, v137, vcc
	v_cmp_class_f32_e32 vcc, v123, v189
	s_nop 1
	v_cndmask_b32_e32 v123, v136, v123, vcc
	v_div_scale_f32 v136, s[0:1], v123, v123, 1.0
	v_rcp_f32_e32 v137, v136
	s_nop 0
	v_fma_f32 v138, -v136, v137, 1.0
	v_fmac_f32_e32 v137, v138, v137
	v_div_scale_f32 v138, vcc, 1.0, v123, 1.0
	v_mul_f32_e32 v139, v138, v137
	v_fma_f32 v140, -v136, v139, v138
	v_fmac_f32_e32 v139, v140, v137
	v_fma_f32 v136, -v136, v139, v138
	v_div_fmas_f32 v136, v136, v137, v139
	v_div_fixup_f32 v123, v136, v123, 1.0
	v_mul_f32_e32 v0, v0, v123
	v_mul_f32_e32 v87, v87, v123
	v_mul_f32_e32 v121, v121, v123
	v_mul_f32_e32 v122, v122, v123
	v_fma_f32 v81, v3, v122, v81
	v_fma_f32 v80, v2, v121, v80
	v_fma_f32 v79, v5, v87, v79
	v_fmac_f32_e32 v78, v4, v0
	global_store_dwordx4 v[104:105], v[78:81], off nt
	v_mul_f32_e32 v0, v130, v123
	v_fmac_f32_e32 v74, v8, v0
	v_mul_f32_e32 v78, v124, v123
	v_mul_f32_e32 v79, v131, v123
	v_mul_f32_e32 v80, v125, v123
	v_fma_f32 v77, v7, v80, v77
	v_fma_f32 v76, v6, v79, v76
	v_fma_f32 v75, v9, v78, v75
	global_store_dwordx4 v[104:105], v[74:77], off offset:1024 nt
	v_mul_f32_e32 v0, v132, v123
	v_fmac_f32_e32 v70, v12, v0
	v_mul_f32_e32 v74, v126, v123
	v_mul_f32_e32 v75, v133, v123
	v_mul_f32_e32 v76, v127, v123
	v_fma_f32 v73, v11, v76, v73
	v_fma_f32 v72, v10, v75, v72
	v_fma_f32 v71, v13, v74, v71
	global_store_dwordx4 v[104:105], v[70:73], off offset:2048 nt
	v_mul_f32_e32 v0, v134, v123
	v_fmac_f32_e32 v66, v16, v0
	v_mul_f32_e32 v70, v128, v123
	v_mul_f32_e32 v71, v135, v123
	v_mul_f32_e32 v72, v129, v123
	v_fma_f32 v69, v15, v72, v69
	v_fma_f32 v68, v14, v71, v68
	v_fma_f32 v67, v17, v70, v67
	global_store_dwordx4 v[104:105], v[66:69], off offset:3072 nt
	s_waitcnt vmcnt(26)
	v_lshlrev_b32_e32 v0, 16, v150
	s_waitcnt vmcnt(24)
	v_and_b32_e32 v71, 0xffff0000, v152
	v_and_b32_e32 v66, 0xffff0000, v150
	v_and_b32_e32 v68, 0xffff0000, v151
	v_lshlrev_b32_e32 v67, 16, v151
	v_mul_f32_e32 v69, v66, v66
	v_mul_f32_e32 v70, v68, v68
	v_fmac_f32_e32 v69, v0, v0
	v_fmac_f32_e32 v70, v67, v67
	v_and_b32_e32 v73, 0xffff0000, v153
	v_add_f32_e32 v69, v69, v70
	v_lshlrev_b32_e32 v70, 16, v152
	v_lshlrev_b32_e32 v72, 16, v153
	v_mul_f32_e32 v74, v71, v71
	v_mul_f32_e32 v75, v73, v73
	v_fmac_f32_e32 v74, v70, v70
	v_fmac_f32_e32 v75, v72, v72
	v_add_f32_e32 v74, v74, v75
	s_waitcnt vmcnt(22)
	v_and_b32_e32 v75, 0xffff0000, v154
	v_and_b32_e32 v77, 0xffff0000, v155
	v_add_f32_e32 v69, v69, v74
	v_lshlrev_b32_e32 v74, 16, v154
	v_lshlrev_b32_e32 v76, 16, v155
	v_mul_f32_e32 v78, v75, v75
	v_mul_f32_e32 v79, v77, v77
	v_fmac_f32_e32 v78, v74, v74
	v_fmac_f32_e32 v79, v76, v76
	v_add_f32_e32 v78, v78, v79
	s_waitcnt vmcnt(20)
	v_and_b32_e32 v79, 0xffff0000, v156
	v_and_b32_e32 v81, 0xffff0000, v157
	v_add_f32_e32 v69, v69, v78
	v_lshlrev_b32_e32 v78, 16, v156
	v_lshlrev_b32_e32 v80, 16, v157
	v_mul_f32_e32 v87, v79, v79
	v_mul_f32_e32 v104, v81, v81
	v_fmac_f32_e32 v87, v78, v78
	v_fmac_f32_e32 v104, v80, v80
	v_add_f32_e32 v87, v87, v104
	v_add_f32_e32 v69, v69, v87
	s_nop 1
	v_add_f32_dpp v69, v69, v69 quad_perm:[1,0,3,2] row_mask:0xf bank_mask:0xf bound_ctrl:1
	s_nop 1
	v_add_f32_dpp v69, v69, v69 quad_perm:[2,3,0,1] row_mask:0xf bank_mask:0xf bound_ctrl:1
	s_nop 1
	v_add_f32_dpp v69, v69, v69 row_half_mirror row_mask:0xf bank_mask:0xf bound_ctrl:1
	s_nop 1
	v_add_f32_dpp v69, v69, v69 row_mirror row_mask:0xf bank_mask:0xf bound_ctrl:1
	s_nop 0
	v_readlane_b32 s1, v69, 16
	v_readlane_b32 s6, v69, 48
	v_readlane_b32 s0, v69, 0
	v_readlane_b32 s2, v69, 32
	v_mov_b32_e32 v69, s1
	v_mov_b32_e32 v87, s6
	v_add_f32_e32 v69, s0, v69
	v_add_f32_e32 v87, s2, v87
	v_add_f32_e32 v69, v69, v87
	v_fmamk_f32 v69, v69, 0x3a800000, v188
	v_cmp_gt_f32_e32 vcc, s49, v69
	v_mul_f32_e32 v87, 0x4f800000, v69
	s_nop 0
	v_cndmask_b32_e32 v69, v69, v87, vcc
	v_sqrt_f32_e32 v87, v69
	s_nop 0
	v_add_u32_e32 v104, -1, v87
	v_fma_f32 v105, -v104, v87, v69
	v_cmp_ge_f32_e64 s[0:1], 0, v105
	v_add_u32_e32 v105, 1, v87
	s_nop 0
	v_cndmask_b32_e64 v104, v87, v104, s[0:1]
	v_fma_f32 v87, -v105, v87, v69
	v_cmp_lt_f32_e64 s[0:1], 0, v87
	s_nop 1
	v_cndmask_b32_e64 v87, v104, v105, s[0:1]
	v_mul_f32_e32 v104, 0x37800000, v87
	v_cndmask_b32_e32 v87, v87, v104, vcc
	v_cmp_class_f32_e32 vcc, v69, v189
	s_nop 1
	v_cndmask_b32_e32 v69, v87, v69, vcc
	v_div_scale_f32 v87, s[0:1], v69, v69, 1.0
	v_rcp_f32_e32 v104, v87
	s_nop 0
	v_fma_f32 v105, -v87, v104, 1.0
	v_fmac_f32_e32 v104, v105, v104
	v_div_scale_f32 v105, vcc, 1.0, v69, 1.0
	v_mul_f32_e32 v156, v105, v104
	v_fma_f32 v157, -v87, v156, v105
	v_fmac_f32_e32 v156, v157, v104
	v_fma_f32 v87, -v87, v156, v105
	v_div_fmas_f32 v87, v87, v104, v156
	v_div_fixup_f32 v69, v87, v69, 1.0
	v_mul_f32_e32 v0, v0, v69
	v_mul_f32_e32 v66, v66, v69
	v_mul_f32_e32 v67, v67, v69
	v_mul_f32_e32 v68, v68, v69
	v_fma_f32 v65, v191, v68, v65
	v_fma_f32 v64, v190, v67, v64
	v_fma_f32 v63, v193, v66, v63
	v_fmac_f32_e32 v62, v192, v0
	v_mul_f32_e32 v0, v70, v69
	v_fmac_f32_e32 v58, v196, v0
	v_mul_f32_e32 v212, v71, v69
	v_mul_f32_e32 v213, v72, v69
	v_mul_f32_e32 v214, v73, v69
	v_fma_f32 v61, v195, v214, v61
	v_fma_f32 v60, v194, v213, v60
	v_fma_f32 v59, v197, v212, v59
	v_mul_f32_e32 v0, v74, v69
	v_fmac_f32_e32 v54, v200, v0
	v_mul_f32_e32 v216, v75, v69
	v_mul_f32_e32 v217, v76, v69
	v_mul_f32_e32 v218, v77, v69
	v_fma_f32 v57, v199, v218, v57
	v_fma_f32 v56, v198, v217, v56
	v_fma_f32 v55, v201, v216, v55
	v_mul_f32_e32 v0, v78, v69
	v_fmac_f32_e32 v50, v204, v0
	v_mul_f32_e32 v220, v79, v69
	v_mul_f32_e32 v221, v80, v69
	v_mul_f32_e32 v222, v81, v69
	v_fma_f32 v53, v203, v222, v53
	v_fma_f32 v52, v202, v221, v52
	v_fma_f32 v51, v205, v220, v51
	s_waitcnt vmcnt(26)
	v_lshlrev_b32_e32 v0, 16, v118
	s_waitcnt vmcnt(24)
	v_and_b32_e32 v71, 0xffff0000, v116
	v_and_b32_e32 v66, 0xffff0000, v118
	v_and_b32_e32 v68, 0xffff0000, v119
	v_lshlrev_b32_e32 v67, 16, v119
	v_mul_f32_e32 v69, v66, v66
	v_mul_f32_e32 v70, v68, v68
	v_fmac_f32_e32 v69, v0, v0
	v_fmac_f32_e32 v70, v67, v67
	v_and_b32_e32 v73, 0xffff0000, v117
	v_add_f32_e32 v69, v69, v70
	v_lshlrev_b32_e32 v70, 16, v116
	v_lshlrev_b32_e32 v72, 16, v117
	v_mul_f32_e32 v74, v71, v71
	v_mul_f32_e32 v75, v73, v73
	v_fmac_f32_e32 v74, v70, v70
	v_fmac_f32_e32 v75, v72, v72
	v_add_f32_e32 v74, v74, v75
	s_waitcnt vmcnt(22)
	v_and_b32_e32 v75, 0xffff0000, v114
	v_and_b32_e32 v77, 0xffff0000, v115
	v_add_f32_e32 v69, v69, v74
	v_lshlrev_b32_e32 v74, 16, v114
	v_lshlrev_b32_e32 v76, 16, v115
	v_mul_f32_e32 v78, v75, v75
	v_mul_f32_e32 v79, v77, v77
	v_fmac_f32_e32 v78, v74, v74
	v_fmac_f32_e32 v79, v76, v76
	v_add_f32_e32 v78, v78, v79
	s_waitcnt vmcnt(20)
	v_and_b32_e32 v79, 0xffff0000, v112
	v_and_b32_e32 v81, 0xffff0000, v113
	v_add_f32_e32 v69, v69, v78
	v_lshlrev_b32_e32 v78, 16, v112
	v_lshlrev_b32_e32 v80, 16, v113
	v_mul_f32_e32 v87, v79, v79
	v_mul_f32_e32 v104, v81, v81
	v_fmac_f32_e32 v87, v78, v78
	v_fmac_f32_e32 v104, v80, v80
	v_add_f32_e32 v87, v87, v104
	v_add_f32_e32 v69, v69, v87
	s_nop 1
	v_add_f32_dpp v69, v69, v69 quad_perm:[1,0,3,2] row_mask:0xf bank_mask:0xf bound_ctrl:1
	s_nop 1
	v_add_f32_dpp v69, v69, v69 quad_perm:[2,3,0,1] row_mask:0xf bank_mask:0xf bound_ctrl:1
	s_nop 1
	v_add_f32_dpp v69, v69, v69 row_half_mirror row_mask:0xf bank_mask:0xf bound_ctrl:1
	s_nop 1
	v_add_f32_dpp v69, v69, v69 row_mirror row_mask:0xf bank_mask:0xf bound_ctrl:1
	s_nop 0
	v_readlane_b32 s1, v69, 16
	v_readlane_b32 s6, v69, 48
	v_readlane_b32 s0, v69, 0
	v_readlane_b32 s2, v69, 32
	v_mov_b32_e32 v69, s1
	v_mov_b32_e32 v87, s6
	v_add_f32_e32 v69, s0, v69
	v_add_f32_e32 v87, s2, v87
	v_add_f32_e32 v69, v69, v87
	v_fmamk_f32 v69, v69, 0x3a800000, v188
	v_cmp_gt_f32_e32 vcc, s49, v69
	v_mul_f32_e32 v87, 0x4f800000, v69
	s_nop 0
	v_cndmask_b32_e32 v69, v69, v87, vcc
	v_sqrt_f32_e32 v87, v69
	s_nop 0
	v_add_u32_e32 v104, -1, v87
	v_fma_f32 v105, -v104, v87, v69
	v_cmp_ge_f32_e64 s[0:1], 0, v105
	v_add_u32_e32 v105, 1, v87
	s_nop 0
	v_cndmask_b32_e64 v104, v87, v104, s[0:1]
	v_fma_f32 v87, -v105, v87, v69
	v_cmp_lt_f32_e64 s[0:1], 0, v87
	s_nop 1
	v_cndmask_b32_e64 v87, v104, v105, s[0:1]
	v_mul_f32_e32 v104, 0x37800000, v87
	v_cndmask_b32_e32 v87, v87, v104, vcc
	v_cmp_class_f32_e32 vcc, v69, v189
	s_nop 1
	v_cndmask_b32_e32 v69, v87, v69, vcc
	v_div_scale_f32 v87, s[0:1], v69, v69, 1.0
	v_rcp_f32_e32 v104, v87
	s_nop 0
	v_fma_f32 v105, -v87, v104, 1.0
	v_fmac_f32_e32 v104, v105, v104
	v_div_scale_f32 v105, vcc, 1.0, v69, 1.0
	v_mul_f32_e32 v112, v105, v104
	v_fma_f32 v113, -v87, v112, v105
	v_fmac_f32_e32 v112, v113, v104
	v_fma_f32 v87, -v87, v112, v105
	v_div_fmas_f32 v87, v87, v104, v112
	v_div_fixup_f32 v69, v87, v69, 1.0
	v_mul_f32_e32 v0, v0, v69
	v_mul_f32_e32 v66, v66, v69
	v_mul_f32_e32 v67, v67, v69
	v_mul_f32_e32 v68, v68, v69
	v_fma_f32 v65, v3, v68, v65
	v_fma_f32 v64, v2, v67, v64
	v_fma_f32 v63, v5, v66, v63
	v_fmac_f32_e32 v62, v4, v0
	global_store_dwordx4 v[94:95], v[62:65], off nt
	v_mul_f32_e32 v0, v70, v69
	v_fmac_f32_e32 v58, v8, v0
	v_mul_f32_e32 v62, v71, v69
	v_mul_f32_e32 v63, v72, v69
	v_mul_f32_e32 v64, v73, v69
	v_fma_f32 v61, v7, v64, v61
	v_fma_f32 v60, v6, v63, v60
	v_fma_f32 v59, v9, v62, v59
	global_store_dwordx4 v[94:95], v[58:61], off offset:1024 nt
	v_mul_f32_e32 v0, v74, v69
	v_fmac_f32_e32 v54, v12, v0
	v_mul_f32_e32 v58, v75, v69
	v_mul_f32_e32 v59, v76, v69
	v_mul_f32_e32 v60, v77, v69
	v_fma_f32 v57, v11, v60, v57
	v_fma_f32 v56, v10, v59, v56
	v_fma_f32 v55, v13, v58, v55
	global_store_dwordx4 v[94:95], v[54:57], off offset:2048 nt
	v_mul_f32_e32 v0, v78, v69
	v_fmac_f32_e32 v50, v16, v0
	v_mul_f32_e32 v54, v79, v69
	v_mul_f32_e32 v55, v80, v69
	v_mul_f32_e32 v56, v81, v69
	v_fma_f32 v53, v15, v56, v53
	v_fma_f32 v52, v14, v55, v52
	v_fma_f32 v51, v17, v54, v51
	global_store_dwordx4 v[94:95], v[50:53], off offset:3072 nt
	s_waitcnt vmcnt(22)
	v_lshlrev_b32_e32 v0, 16, v158
	s_waitcnt vmcnt(20)
	v_and_b32_e32 v55, 0xffff0000, v160
	v_and_b32_e32 v50, 0xffff0000, v158
	v_and_b32_e32 v52, 0xffff0000, v159
	v_lshlrev_b32_e32 v51, 16, v159
	v_mul_f32_e32 v53, v50, v50
	v_mul_f32_e32 v54, v52, v52
	v_fmac_f32_e32 v53, v0, v0
	v_fmac_f32_e32 v54, v51, v51
	v_and_b32_e32 v57, 0xffff0000, v161
	v_add_f32_e32 v53, v53, v54
	v_lshlrev_b32_e32 v54, 16, v160
	v_lshlrev_b32_e32 v56, 16, v161
	v_mul_f32_e32 v58, v55, v55
	v_mul_f32_e32 v59, v57, v57
	v_fmac_f32_e32 v58, v54, v54
	v_fmac_f32_e32 v59, v56, v56
	v_add_f32_e32 v58, v58, v59
	s_waitcnt vmcnt(18)
	v_and_b32_e32 v59, 0xffff0000, v162
	v_and_b32_e32 v61, 0xffff0000, v163
	v_add_f32_e32 v53, v53, v58
	v_lshlrev_b32_e32 v58, 16, v162
	v_lshlrev_b32_e32 v60, 16, v163
	v_mul_f32_e32 v62, v59, v59
	v_mul_f32_e32 v63, v61, v61
	v_fmac_f32_e32 v62, v58, v58
	v_fmac_f32_e32 v63, v60, v60
	v_add_f32_e32 v62, v62, v63
	s_waitcnt vmcnt(16)
	v_and_b32_e32 v63, 0xffff0000, v164
	v_and_b32_e32 v65, 0xffff0000, v165
	v_add_f32_e32 v53, v53, v62
	v_lshlrev_b32_e32 v62, 16, v164
	v_lshlrev_b32_e32 v64, 16, v165
	v_mul_f32_e32 v66, v63, v63
	v_mul_f32_e32 v67, v65, v65
	v_fmac_f32_e32 v66, v62, v62
	v_fmac_f32_e32 v67, v64, v64
	v_add_f32_e32 v66, v66, v67
	v_add_f32_e32 v53, v53, v66
	s_nop 1
	v_add_f32_dpp v53, v53, v53 quad_perm:[1,0,3,2] row_mask:0xf bank_mask:0xf bound_ctrl:1
	s_nop 1
	v_add_f32_dpp v53, v53, v53 quad_perm:[2,3,0,1] row_mask:0xf bank_mask:0xf bound_ctrl:1
	s_nop 1
	v_add_f32_dpp v53, v53, v53 row_half_mirror row_mask:0xf bank_mask:0xf bound_ctrl:1
	s_nop 1
	v_add_f32_dpp v53, v53, v53 row_mirror row_mask:0xf bank_mask:0xf bound_ctrl:1
	s_nop 0
	v_readlane_b32 s1, v53, 16
	v_readlane_b32 s6, v53, 48
	v_readlane_b32 s0, v53, 0
	v_readlane_b32 s2, v53, 32
	v_mov_b32_e32 v53, s1
	v_mov_b32_e32 v66, s6
	v_add_f32_e32 v53, s0, v53
	v_add_f32_e32 v66, s2, v66
	v_add_f32_e32 v53, v53, v66
	v_fmamk_f32 v53, v53, 0x3a800000, v188
	v_cmp_gt_f32_e32 vcc, s49, v53
	v_mul_f32_e32 v66, 0x4f800000, v53
	s_nop 0
	v_cndmask_b32_e32 v53, v53, v66, vcc
	v_sqrt_f32_e32 v66, v53
	s_nop 0
	v_add_u32_e32 v67, -1, v66
	v_fma_f32 v68, -v67, v66, v53
	v_cmp_ge_f32_e64 s[0:1], 0, v68
	v_add_u32_e32 v68, 1, v66
	s_nop 0
	v_cndmask_b32_e64 v67, v66, v67, s[0:1]
	v_fma_f32 v66, -v68, v66, v53
	v_cmp_lt_f32_e64 s[0:1], 0, v66
	s_nop 1
	v_cndmask_b32_e64 v66, v67, v68, s[0:1]
	v_mul_f32_e32 v67, 0x37800000, v66
	v_cndmask_b32_e32 v66, v66, v67, vcc
	v_cmp_class_f32_e32 vcc, v53, v189
	s_nop 1
	v_cndmask_b32_e32 v53, v66, v53, vcc
	v_div_scale_f32 v66, s[0:1], v53, v53, 1.0
	v_rcp_f32_e32 v67, v66
	s_nop 0
	v_fma_f32 v68, -v66, v67, 1.0
	v_fmac_f32_e32 v67, v68, v67
	v_div_scale_f32 v68, vcc, 1.0, v53, 1.0
	v_mul_f32_e32 v69, v68, v67
	v_fma_f32 v70, -v66, v69, v68
	v_fmac_f32_e32 v69, v70, v67
	v_fma_f32 v66, -v66, v69, v68
	v_div_fmas_f32 v66, v66, v67, v69
	v_div_fixup_f32 v53, v66, v53, 1.0
	v_mul_f32_e32 v0, v0, v53
	v_mul_f32_e32 v50, v50, v53
	v_mul_f32_e32 v51, v51, v53
	v_mul_f32_e32 v52, v52, v53
	v_fma_f32 v49, v191, v52, v49
	v_fma_f32 v48, v190, v51, v48
	v_fma_f32 v47, v193, v50, v47
	v_fmac_f32_e32 v46, v192, v0
	v_mul_f32_e32 v0, v54, v53
	v_fmac_f32_e32 v42, v196, v0
	v_mul_f32_e32 v212, v55, v53
	v_mul_f32_e32 v213, v56, v53
	v_mul_f32_e32 v214, v57, v53
	v_fma_f32 v45, v195, v214, v45
	v_fma_f32 v44, v194, v213, v44
	v_fma_f32 v43, v197, v212, v43
	v_mul_f32_e32 v0, v58, v53
	v_fmac_f32_e32 v38, v200, v0
	v_mul_f32_e32 v216, v59, v53
	v_mul_f32_e32 v217, v60, v53
	v_mul_f32_e32 v218, v61, v53
	v_fma_f32 v41, v199, v218, v41
	v_fma_f32 v40, v198, v217, v40
	v_fma_f32 v39, v201, v216, v39
	v_mul_f32_e32 v0, v62, v53
	v_fmac_f32_e32 v34, v204, v0
	v_mul_f32_e32 v220, v63, v53
	v_mul_f32_e32 v221, v64, v53
	v_mul_f32_e32 v222, v65, v53
	v_fma_f32 v37, v203, v222, v37
	v_fma_f32 v36, v202, v221, v36
	v_fma_f32 v35, v205, v220, v35
	s_waitcnt vmcnt(22)
	v_lshlrev_b32_e32 v0, 16, v110
	s_waitcnt vmcnt(20)
	v_and_b32_e32 v55, 0xffff0000, v108
	v_and_b32_e32 v50, 0xffff0000, v110
	v_and_b32_e32 v52, 0xffff0000, v111
	v_lshlrev_b32_e32 v51, 16, v111
	v_mul_f32_e32 v53, v50, v50
	v_mul_f32_e32 v54, v52, v52
	v_fmac_f32_e32 v53, v0, v0
	v_fmac_f32_e32 v54, v51, v51
	v_and_b32_e32 v57, 0xffff0000, v109
	v_add_f32_e32 v53, v53, v54
	v_lshlrev_b32_e32 v54, 16, v108
	v_lshlrev_b32_e32 v56, 16, v109
	v_mul_f32_e32 v58, v55, v55
	v_mul_f32_e32 v59, v57, v57
	v_fmac_f32_e32 v58, v54, v54
	v_fmac_f32_e32 v59, v56, v56
	v_add_f32_e32 v58, v58, v59
	s_waitcnt vmcnt(18)
	v_and_b32_e32 v59, 0xffff0000, v106
	v_and_b32_e32 v61, 0xffff0000, v107
	v_add_f32_e32 v53, v53, v58
	v_lshlrev_b32_e32 v58, 16, v106
	v_lshlrev_b32_e32 v60, 16, v107
	v_mul_f32_e32 v62, v59, v59
	v_mul_f32_e32 v63, v61, v61
	v_fmac_f32_e32 v62, v58, v58
	v_fmac_f32_e32 v63, v60, v60
	v_add_f32_e32 v62, v62, v63
	s_waitcnt vmcnt(16)
	v_and_b32_e32 v63, 0xffff0000, v102
	v_and_b32_e32 v65, 0xffff0000, v103
	v_add_f32_e32 v53, v53, v62
	v_lshlrev_b32_e32 v62, 16, v102
	v_lshlrev_b32_e32 v64, 16, v103
	v_mul_f32_e32 v66, v63, v63
	v_mul_f32_e32 v67, v65, v65
	v_fmac_f32_e32 v66, v62, v62
	v_fmac_f32_e32 v67, v64, v64
	v_add_f32_e32 v66, v66, v67
	v_add_f32_e32 v53, v53, v66
	s_nop 1
	v_add_f32_dpp v53, v53, v53 quad_perm:[1,0,3,2] row_mask:0xf bank_mask:0xf bound_ctrl:1
	s_nop 1
	v_add_f32_dpp v53, v53, v53 quad_perm:[2,3,0,1] row_mask:0xf bank_mask:0xf bound_ctrl:1
	s_nop 1
	v_add_f32_dpp v53, v53, v53 row_half_mirror row_mask:0xf bank_mask:0xf bound_ctrl:1
	s_nop 1
	v_add_f32_dpp v53, v53, v53 row_mirror row_mask:0xf bank_mask:0xf bound_ctrl:1
	s_nop 0
	v_readlane_b32 s1, v53, 16
	v_readlane_b32 s6, v53, 48
	v_readlane_b32 s0, v53, 0
	v_readlane_b32 s2, v53, 32
	v_mov_b32_e32 v53, s1
	v_mov_b32_e32 v66, s6
	v_add_f32_e32 v53, s0, v53
	v_add_f32_e32 v66, s2, v66
	v_add_f32_e32 v53, v53, v66
	v_fmamk_f32 v53, v53, 0x3a800000, v188
	v_cmp_gt_f32_e32 vcc, s49, v53
	v_mul_f32_e32 v66, 0x4f800000, v53
	s_nop 0
	v_cndmask_b32_e32 v53, v53, v66, vcc
	v_sqrt_f32_e32 v66, v53
	s_nop 0
	v_add_u32_e32 v67, -1, v66
	v_fma_f32 v68, -v67, v66, v53
	v_cmp_ge_f32_e64 s[0:1], 0, v68
	v_add_u32_e32 v68, 1, v66
	s_nop 0
	v_cndmask_b32_e64 v67, v66, v67, s[0:1]
	v_fma_f32 v66, -v68, v66, v53
	v_cmp_lt_f32_e64 s[0:1], 0, v66
	s_nop 1
	v_cndmask_b32_e64 v66, v67, v68, s[0:1]
	v_mul_f32_e32 v67, 0x37800000, v66
	v_cndmask_b32_e32 v66, v66, v67, vcc
	v_cmp_class_f32_e32 vcc, v53, v189
	s_nop 1
	v_cndmask_b32_e32 v53, v66, v53, vcc
	v_div_scale_f32 v66, s[0:1], v53, v53, 1.0
	v_rcp_f32_e32 v67, v66
	s_nop 0
	v_fma_f32 v68, -v66, v67, 1.0
	v_fmac_f32_e32 v67, v68, v67
	v_div_scale_f32 v68, vcc, 1.0, v53, 1.0
	v_mul_f32_e32 v69, v68, v67
	v_fma_f32 v70, -v66, v69, v68
	v_fmac_f32_e32 v69, v70, v67
	v_fma_f32 v66, -v66, v69, v68
	v_div_fmas_f32 v66, v66, v67, v69
	v_div_fixup_f32 v53, v66, v53, 1.0
	v_mul_f32_e32 v0, v0, v53
	v_mul_f32_e32 v50, v50, v53
	v_mul_f32_e32 v51, v51, v53
	v_mul_f32_e32 v52, v52, v53
	v_fma_f32 v49, v3, v52, v49
	v_fma_f32 v48, v2, v51, v48
	v_fma_f32 v47, v5, v50, v47
	v_fmac_f32_e32 v46, v4, v0
	global_store_dwordx4 v[90:91], v[46:49], off nt
	v_mul_f32_e32 v0, v54, v53
	v_fmac_f32_e32 v42, v8, v0
	v_mul_f32_e32 v46, v55, v53
	v_mul_f32_e32 v47, v56, v53
	v_mul_f32_e32 v48, v57, v53
	v_fma_f32 v45, v7, v48, v45
	v_fma_f32 v44, v6, v47, v44
	v_fma_f32 v43, v9, v46, v43
	global_store_dwordx4 v[90:91], v[42:45], off offset:1024 nt
	v_mul_f32_e32 v0, v58, v53
	v_fmac_f32_e32 v38, v12, v0
	v_mul_f32_e32 v42, v59, v53
	v_mul_f32_e32 v43, v60, v53
	v_mul_f32_e32 v44, v61, v53
	v_fma_f32 v41, v11, v44, v41
	v_fma_f32 v40, v10, v43, v40
	v_fma_f32 v39, v13, v42, v39
	global_store_dwordx4 v[90:91], v[38:41], off offset:2048 nt
	v_mul_f32_e32 v0, v62, v53
	v_fmac_f32_e32 v34, v16, v0
	v_mul_f32_e32 v38, v63, v53
	v_mul_f32_e32 v39, v64, v53
	v_mul_f32_e32 v40, v65, v53
	v_fma_f32 v37, v15, v40, v37
	v_fma_f32 v36, v14, v39, v36
	v_fma_f32 v35, v17, v38, v35
	global_store_dwordx4 v[90:91], v[34:37], off offset:3072 nt
	s_waitcnt vmcnt(18)
	v_lshlrev_b32_e32 v0, 16, v166
	s_waitcnt vmcnt(16)
	v_and_b32_e32 v39, 0xffff0000, v168
	v_and_b32_e32 v34, 0xffff0000, v166
	v_and_b32_e32 v36, 0xffff0000, v167
	v_lshlrev_b32_e32 v35, 16, v167
	v_mul_f32_e32 v37, v34, v34
	v_mul_f32_e32 v38, v36, v36
	v_fmac_f32_e32 v37, v0, v0
	v_fmac_f32_e32 v38, v35, v35
	v_and_b32_e32 v41, 0xffff0000, v169
	v_add_f32_e32 v37, v37, v38
	v_lshlrev_b32_e32 v38, 16, v168
	v_lshlrev_b32_e32 v40, 16, v169
	v_mul_f32_e32 v42, v39, v39
	v_mul_f32_e32 v43, v41, v41
	v_fmac_f32_e32 v42, v38, v38
	v_fmac_f32_e32 v43, v40, v40
	v_add_f32_e32 v42, v42, v43
	s_waitcnt vmcnt(14)
	v_and_b32_e32 v43, 0xffff0000, v170
	v_and_b32_e32 v45, 0xffff0000, v171
	v_add_f32_e32 v37, v37, v42
	v_lshlrev_b32_e32 v42, 16, v170
	v_lshlrev_b32_e32 v44, 16, v171
	v_mul_f32_e32 v46, v43, v43
	v_mul_f32_e32 v47, v45, v45
	v_fmac_f32_e32 v46, v42, v42
	v_fmac_f32_e32 v47, v44, v44
	v_add_f32_e32 v46, v46, v47
	s_waitcnt vmcnt(12)
	v_and_b32_e32 v47, 0xffff0000, v172
	v_and_b32_e32 v49, 0xffff0000, v173
	v_add_f32_e32 v37, v37, v46
	v_lshlrev_b32_e32 v46, 16, v172
	v_lshlrev_b32_e32 v48, 16, v173
	v_mul_f32_e32 v50, v47, v47
	v_mul_f32_e32 v51, v49, v49
	v_fmac_f32_e32 v50, v46, v46
	v_fmac_f32_e32 v51, v48, v48
	v_add_f32_e32 v50, v50, v51
	v_add_f32_e32 v37, v37, v50
	s_nop 1
	v_add_f32_dpp v37, v37, v37 quad_perm:[1,0,3,2] row_mask:0xf bank_mask:0xf bound_ctrl:1
	s_nop 1
	v_add_f32_dpp v37, v37, v37 quad_perm:[2,3,0,1] row_mask:0xf bank_mask:0xf bound_ctrl:1
	s_nop 1
	v_add_f32_dpp v37, v37, v37 row_half_mirror row_mask:0xf bank_mask:0xf bound_ctrl:1
	s_nop 1
	v_add_f32_dpp v37, v37, v37 row_mirror row_mask:0xf bank_mask:0xf bound_ctrl:1
	s_nop 0
	v_readlane_b32 s1, v37, 16
	v_readlane_b32 s6, v37, 48
	v_readlane_b32 s0, v37, 0
	v_readlane_b32 s2, v37, 32
	v_mov_b32_e32 v37, s1
	v_mov_b32_e32 v50, s6
	v_add_f32_e32 v37, s0, v37
	v_add_f32_e32 v50, s2, v50
	v_add_f32_e32 v37, v37, v50
	v_fmamk_f32 v37, v37, 0x3a800000, v188
	v_cmp_gt_f32_e32 vcc, s49, v37
	v_mul_f32_e32 v50, 0x4f800000, v37
	s_nop 0
	v_cndmask_b32_e32 v37, v37, v50, vcc
	v_sqrt_f32_e32 v50, v37
	s_nop 0
	v_add_u32_e32 v51, -1, v50
	v_fma_f32 v52, -v51, v50, v37
	v_cmp_ge_f32_e64 s[0:1], 0, v52
	v_add_u32_e32 v52, 1, v50
	s_nop 0
	v_cndmask_b32_e64 v51, v50, v51, s[0:1]
	v_fma_f32 v50, -v52, v50, v37
	v_cmp_lt_f32_e64 s[0:1], 0, v50
	s_nop 1
	v_cndmask_b32_e64 v50, v51, v52, s[0:1]
	v_mul_f32_e32 v51, 0x37800000, v50
	v_cndmask_b32_e32 v50, v50, v51, vcc
	v_cmp_class_f32_e32 vcc, v37, v189
	s_nop 1
	v_cndmask_b32_e32 v37, v50, v37, vcc
	v_div_scale_f32 v50, s[0:1], v37, v37, 1.0
	v_rcp_f32_e32 v51, v50
	s_nop 0
	v_fma_f32 v52, -v50, v51, 1.0
	v_fmac_f32_e32 v51, v52, v51
	v_div_scale_f32 v52, vcc, 1.0, v37, 1.0
	v_mul_f32_e32 v53, v52, v51
	v_fma_f32 v54, -v50, v53, v52
	v_fmac_f32_e32 v53, v54, v51
	v_fma_f32 v50, -v50, v53, v52
	v_div_fmas_f32 v50, v50, v51, v53
	v_div_fixup_f32 v37, v50, v37, 1.0
	v_mul_f32_e32 v0, v0, v37
	v_mul_f32_e32 v34, v34, v37
	v_mul_f32_e32 v35, v35, v37
	v_mul_f32_e32 v36, v36, v37
	v_fma_f32 v33, v191, v36, v33
	v_fma_f32 v32, v190, v35, v32
	v_fma_f32 v31, v193, v34, v31
	v_fmac_f32_e32 v30, v192, v0
	v_mul_f32_e32 v0, v38, v37
	v_fmac_f32_e32 v26, v196, v0
	v_mul_f32_e32 v212, v39, v37
	v_mul_f32_e32 v213, v40, v37
	v_mul_f32_e32 v214, v41, v37
	v_fma_f32 v29, v195, v214, v29
	v_fma_f32 v28, v194, v213, v28
	v_fma_f32 v27, v197, v212, v27
	v_mul_f32_e32 v0, v42, v37
	v_fmac_f32_e32 v22, v200, v0
	v_mul_f32_e32 v216, v43, v37
	v_mul_f32_e32 v217, v44, v37
	v_mul_f32_e32 v218, v45, v37
	v_fma_f32 v25, v199, v218, v25
	v_fma_f32 v24, v198, v217, v24
	v_fma_f32 v23, v201, v216, v23
	v_mul_f32_e32 v0, v46, v37
	v_cmp_lt_i32_e32 vcc, s61, v120
	v_mul_f32_e32 v220, v47, v37
	v_mul_f32_e32 v221, v48, v37
	v_mul_f32_e32 v222, v49, v37
	v_fma_f32 v21, v203, v222, v21
	v_fma_f32 v20, v202, v221, v20
	v_fma_f32 v19, v205, v220, v19
	v_fmac_f32_e32 v18, v204, v0
	s_or_b64 s[34:35], vcc, s[34:35]
	s_waitcnt vmcnt(18)
	v_lshlrev_b32_e32 v0, 16, v100
	s_waitcnt vmcnt(16)
	v_and_b32_e32 v39, 0xffff0000, v98
	v_and_b32_e32 v34, 0xffff0000, v100
	v_and_b32_e32 v36, 0xffff0000, v101
	v_lshlrev_b32_e32 v35, 16, v101
	v_mul_f32_e32 v37, v34, v34
	v_mul_f32_e32 v38, v36, v36
	v_fmac_f32_e32 v37, v0, v0
	v_fmac_f32_e32 v38, v35, v35
	v_and_b32_e32 v41, 0xffff0000, v99
	v_add_f32_e32 v37, v37, v38
	v_lshlrev_b32_e32 v38, 16, v98
	v_lshlrev_b32_e32 v40, 16, v99
	v_mul_f32_e32 v42, v39, v39
	v_mul_f32_e32 v43, v41, v41
	v_fmac_f32_e32 v42, v38, v38
	v_fmac_f32_e32 v43, v40, v40
	v_add_f32_e32 v42, v42, v43
	s_waitcnt vmcnt(14)
	v_and_b32_e32 v43, 0xffff0000, v96
	v_and_b32_e32 v45, 0xffff0000, v97
	v_add_f32_e32 v37, v37, v42
	v_lshlrev_b32_e32 v42, 16, v96
	v_lshlrev_b32_e32 v44, 16, v97
	v_mul_f32_e32 v46, v43, v43
	v_mul_f32_e32 v47, v45, v45
	v_fmac_f32_e32 v46, v42, v42
	v_fmac_f32_e32 v47, v44, v44
	v_add_f32_e32 v46, v46, v47
	s_waitcnt vmcnt(12)
	v_and_b32_e32 v47, 0xffff0000, v92
	v_and_b32_e32 v49, 0xffff0000, v93
	v_add_f32_e32 v37, v37, v46
	v_lshlrev_b32_e32 v46, 16, v92
	v_lshlrev_b32_e32 v48, 16, v93
	v_mul_f32_e32 v50, v47, v47
	v_mul_f32_e32 v51, v49, v49
	v_fmac_f32_e32 v50, v46, v46
	v_fmac_f32_e32 v51, v48, v48
	v_add_f32_e32 v50, v50, v51
	v_add_f32_e32 v37, v37, v50
	s_nop 1
	v_add_f32_dpp v37, v37, v37 quad_perm:[1,0,3,2] row_mask:0xf bank_mask:0xf bound_ctrl:1
	s_nop 1
	v_add_f32_dpp v37, v37, v37 quad_perm:[2,3,0,1] row_mask:0xf bank_mask:0xf bound_ctrl:1
	s_nop 1
	v_add_f32_dpp v37, v37, v37 row_half_mirror row_mask:0xf bank_mask:0xf bound_ctrl:1
	s_nop 1
	v_add_f32_dpp v37, v37, v37 row_mirror row_mask:0xf bank_mask:0xf bound_ctrl:1
	s_nop 0
	v_readlane_b32 s1, v37, 16
	v_readlane_b32 s6, v37, 48
	v_readlane_b32 s0, v37, 0
	v_readlane_b32 s2, v37, 32
	v_mov_b32_e32 v37, s1
	v_mov_b32_e32 v50, s6
	v_add_f32_e32 v37, s0, v37
	v_add_f32_e32 v50, s2, v50
	v_add_f32_e32 v37, v37, v50
	v_fmamk_f32 v37, v37, 0x3a800000, v188
	v_cmp_gt_f32_e32 vcc, s49, v37
	v_mul_f32_e32 v50, 0x4f800000, v37
	s_nop 0
	v_cndmask_b32_e32 v37, v37, v50, vcc
	v_sqrt_f32_e32 v50, v37
	s_nop 0
	v_add_u32_e32 v51, -1, v50
	v_fma_f32 v52, -v51, v50, v37
	v_cmp_ge_f32_e64 s[0:1], 0, v52
	v_add_u32_e32 v52, 1, v50
	s_nop 0
	v_cndmask_b32_e64 v51, v50, v51, s[0:1]
	v_fma_f32 v50, -v52, v50, v37
	v_cmp_lt_f32_e64 s[0:1], 0, v50
	s_nop 1
	v_cndmask_b32_e64 v50, v51, v52, s[0:1]
	v_mul_f32_e32 v51, 0x37800000, v50
	v_cndmask_b32_e32 v50, v50, v51, vcc
	v_cmp_class_f32_e32 vcc, v37, v189
	s_nop 1
	v_cndmask_b32_e32 v37, v50, v37, vcc
	v_div_scale_f32 v50, s[0:1], v37, v37, 1.0
	v_rcp_f32_e32 v51, v50
	s_nop 0
	v_fma_f32 v52, -v50, v51, 1.0
	v_fmac_f32_e32 v51, v52, v51
	v_div_scale_f32 v52, vcc, 1.0, v37, 1.0
	v_mul_f32_e32 v53, v52, v51
	v_fma_f32 v54, -v50, v53, v52
	v_fmac_f32_e32 v53, v54, v51
	v_fma_f32 v50, -v50, v53, v52
	v_div_fmas_f32 v50, v50, v51, v53
	v_div_fixup_f32 v37, v50, v37, 1.0
	v_mul_f32_e32 v0, v0, v37
	v_mul_f32_e32 v34, v34, v37
	v_mul_f32_e32 v35, v35, v37
	v_mul_f32_e32 v36, v36, v37
	v_fma_f32 v33, v3, v36, v33
	v_fma_f32 v32, v2, v35, v32
	v_fma_f32 v31, v5, v34, v31
	v_fmac_f32_e32 v30, v4, v0
	global_store_dwordx4 v[88:89], v[30:33], off nt
	v_mul_f32_e32 v0, v38, v37
	v_fmac_f32_e32 v26, v8, v0
	v_mul_f32_e32 v30, v39, v37
	v_mul_f32_e32 v31, v40, v37
	v_mul_f32_e32 v32, v41, v37
	v_fma_f32 v29, v7, v32, v29
	v_fma_f32 v28, v6, v31, v28
	v_fma_f32 v27, v9, v30, v27
	global_store_dwordx4 v[88:89], v[26:29], off offset:1024 nt
	v_mul_f32_e32 v0, v42, v37
	v_fmac_f32_e32 v22, v12, v0
	v_mul_f32_e32 v26, v43, v37
	v_mul_f32_e32 v27, v44, v37
	v_mul_f32_e32 v28, v45, v37
	v_fma_f32 v25, v11, v28, v25
	v_fma_f32 v24, v10, v27, v24
	v_fma_f32 v23, v13, v26, v23
	global_store_dwordx4 v[88:89], v[22:25], off offset:2048 nt
	v_mul_f32_e32 v0, v46, v37
	v_cmp_lt_i32_e32 vcc, s61, v120
	v_mul_f32_e32 v22, v47, v37
	v_mul_f32_e32 v23, v48, v37
	v_mul_f32_e32 v24, v49, v37
	v_fma_f32 v21, v15, v24, v21
	v_fma_f32 v20, v14, v23, v20
	v_fma_f32 v19, v17, v22, v19
	v_fmac_f32_e32 v18, v16, v0
	s_or_b64 s[34:35], vcc, s[34:35]
	global_store_dwordx4 v[88:89], v[18:21], off offset:3072 nt
	s_andn2_b64 exec, exec, s[34:35]
	s_cbranch_execnz .LBB0_28

.LBB0_30:
	s_andn2_b64 vcc, exec, s[0:1]
	s_cbranch_vccnz .LBB0_35
	v_mov_b32_e32 v0, v186
	v_readlane_b32 s0, v255, 16
	v_ashrrev_i32_e32 v2, 6, v0
	v_add_u32_e32 v3, s48, v2
	v_ashrrev_i32_e32 v2, 31, v3
	v_xor_b32_e32 v50, s0, v2
	v_sub_u32_e32 v2, 0, v3
	v_max_i32_e32 v2, v3, v2
	v_mul_hi_u32 v4, v2, v187
	v_readlane_b32 s0, v255, 14
	s_nop 1
	v_mul_lo_u32 v5, v4, s0
	v_sub_u32_e32 v2, v2, v5
	v_add_u32_e32 v5, 1, v4
	v_cmp_le_u32_e32 vcc, s0, v2
	s_nop 1
	v_cndmask_b32_e32 v4, v4, v5, vcc
	v_subrev_u32_e32 v5, s0, v2
	v_cndmask_b32_e32 v2, v2, v5, vcc
	v_add_u32_e32 v5, 1, v4
	v_cmp_le_u32_e32 vcc, s0, v2
	s_movk_i32 s0, 0x400
	s_nop 0
	v_cndmask_b32_e32 v2, v4, v5, vcc
	v_xor_b32_e32 v51, v2, v50
	v_sub_u32_e32 v2, v51, v50
	v_mul_lo_u32 v4, v2, s31
	v_sub_u32_e32 v53, v3, v4
	v_cmp_gt_i32_e32 vcc, s0, v53
	s_and_saveexec_b64 s[38:39], vcc
	s_cbranch_execz .LBB0_34
	v_mov_b64_e32 v[4:5], s[22:23]
	v_mad_i64_i32 v[6:7], s[0:1], v2, s29, v[4:5]
	v_and_b32_e32 v52, 63, v0
	s_mov_b64 s[0:1], 0x2000
	v_add_u32_e32 v0, 8, v2
	v_lshl_add_u64 v[38:39], v[6:7], 0, s[0:1]
	v_mad_i64_i32 v[16:17], s[0:1], v0, s29, v[4:5]
	v_lshlrev_b32_e32 v0, 4, v52
	v_lshl_add_u64 v[2:3], v[38:39], 0, v[0:1]
	global_load_dwordx4 v[4:7], v[2:3], off
	global_load_dwordx4 v[8:11], v0, s[86:87]
	s_mov_b64 s[0:1], 0x1000
	v_lshl_add_u64 v[42:43], v[16:17], 0, s[0:1]
	v_readlane_b32 s0, v253, 31
	v_readlane_b32 s1, v253, 32
	v_or_b32_e32 v24, 0x400, v0
	v_mov_b32_e32 v25, v1
	v_lshl_add_u64 v[46:47], v[16:17], 0, v[0:1]
	v_or_b32_e32 v36, 0x800, v0
	v_mov_b32_e32 v37, v1
	v_or_b32_e32 v44, 0xc00, v0
	v_mov_b32_e32 v45, v1
	s_mov_b32 s2, s64
	v_lshlrev_b32_e32 v172, 2, v53
	s_waitcnt vmcnt(0)
	v_lshl_add_u64 v[120:121], s[88:89], 0, v[0:1]
	v_lshlrev_b32_e32 v52, 3, v52
	v_mov_b32_e32 v53, v1
	v_lshlrev_b32_e32 v50, 12, v50
	v_lshl_add_u64 v[116:117], s[12:13], 0, v[52:53]
	s_mov_b64 s[42:43], 0
	s_waitcnt vmcnt(0)
	v_mul_f32_e32 v3, v7, v11
	v_mul_f32_e32 v2, v6, v10
	v_lshl_add_u64 v[6:7], v[42:43], 0, v[0:1]
	global_load_dwordx4 v[12:15], v[6:7], off
	v_mul_f32_e32 v5, v5, v9
	v_mul_f32_e32 v4, v4, v8
	global_load_dwordx4 v[8:11], v0, s[0:1]
	s_waitcnt vmcnt(1)
	v_add_f32_e32 v12, 1.0, v12
	v_add_f32_e32 v13, 1.0, v13
	v_add_f32_e32 v6, 1.0, v14
	v_add_f32_e32 v7, 1.0, v15
	v_lshl_add_u64 v[14:15], v[38:39], 0, v[24:25]
	s_waitcnt vmcnt(0)
	v_mul_f32_e32 v7, v11, v7
	v_mul_f32_e32 v6, v10, v6
	v_mul_f32_e32 v9, v9, v13
	v_mul_f32_e32 v8, v8, v12
	global_load_dwordx4 v[10:13], v[46:47], off
	global_load_dwordx4 v[16:19], v[14:15], off
	global_load_dwordx4 v[20:23], v0, s[86:87] offset:1024
	s_waitcnt vmcnt(0)
	v_mul_f32_e32 v15, v19, v23
	v_mul_f32_e32 v14, v18, v22
	v_lshl_add_u64 v[18:19], v[42:43], 0, v[24:25]
	v_mul_f32_e32 v17, v17, v21
	v_mul_f32_e32 v16, v16, v20
	global_load_dwordx4 v[20:23], v24, s[0:1]
	s_nop 0
	global_load_dwordx4 v[24:27], v[18:19], off
	s_waitcnt vmcnt(0)
	v_add_f32_e32 v24, 1.0, v24
	v_add_f32_e32 v25, 1.0, v25
	v_add_f32_e32 v18, 1.0, v26
	v_add_f32_e32 v19, 1.0, v27
	v_lshl_add_u64 v[26:27], v[38:39], 0, v[36:37]
	v_mul_f32_e32 v19, v23, v19
	v_mul_f32_e32 v18, v22, v18
	v_mul_f32_e32 v21, v21, v25
	v_mul_f32_e32 v20, v20, v24
	global_load_dwordx4 v[22:25], v[46:47], off offset:1024
	global_load_dwordx4 v[28:31], v[26:27], off
	global_load_dwordx4 v[32:35], v0, s[86:87] offset:2048
	v_lshl_add_u64 v[38:39], v[38:39], 0, v[44:45]
	s_waitcnt vmcnt(0)
	v_mul_f32_e32 v27, v31, v35
	v_mul_f32_e32 v26, v30, v34
	v_lshl_add_u64 v[30:31], v[42:43], 0, v[36:37]
	global_load_dwordx4 v[54:57], v[30:31], off
	v_mul_f32_e32 v29, v29, v33
	v_mul_f32_e32 v28, v28, v32
	global_load_dwordx4 v[32:35], v36, s[0:1]
	v_lshl_add_u64 v[42:43], v[42:43], 0, v[44:45]
	s_waitcnt vmcnt(1)
	v_add_f32_e32 v36, 1.0, v54
	v_add_f32_e32 v37, 1.0, v55
	v_add_f32_e32 v30, 1.0, v56
	v_add_f32_e32 v31, 1.0, v57
	s_waitcnt vmcnt(0)
	v_mul_f32_e32 v31, v35, v31
	v_mul_f32_e32 v30, v34, v30
	v_mul_f32_e32 v33, v33, v37
	v_mul_f32_e32 v32, v32, v36
	global_load_dwordx4 v[34:37], v[46:47], off offset:2048
	global_load_dwordx4 v[54:57], v[38:39], off
	global_load_dwordx4 v[58:61], v0, s[86:87] offset:3072
	s_waitcnt vmcnt(0)
	v_mul_f32_e32 v39, v57, v61
	v_mul_f32_e32 v38, v56, v60
	v_mul_f32_e32 v41, v55, v59
	v_mul_f32_e32 v40, v54, v58
	global_load_dwordx4 v[54:57], v44, s[0:1]
	s_mov_b32 s0, s62
	global_load_dwordx4 v[42:45], v[42:43], off
	s_mov_b32 s1, s63
	v_readlane_b32 s52, v253, 15
	v_readlane_b32 s53, v253, 16
	v_readlane_b32 s62, v253, 25
	v_readlane_b32 s63, v253, 26
	s_mov_b32 s63, s1
	s_mov_b32 s62, s0
	v_lshl_add_u64 v[114:115], s[52:53], 0, v[0:1]
	v_readlane_b32 s0, v255, 8
	v_lshl_add_u32 v0, v51, 12, v172
	v_readlane_b32 s61, v253, 24
	v_readlane_b32 s64, v253, 27
	v_readlane_b32 s1, v255, 9
	v_or_b32_e32 v0, 3, v0
	s_mov_b32 s64, s2
	s_movk_i32 s61, 0xfff
	v_lshl_add_u64 v[118:119], s[0:1], 0, v[52:53]
	v_mov_b64_e32 v[116:117], v[118:119]
	s_add_u32 s0, s0, 0x4000000
	s_addc_u32 s1, s1, 0
	v_lshl_add_u64 v[118:119], s[0:1], 0, v[52:53]
	v_sub_u32_e32 v122, v0, v50
	v_readlane_b32 s54, v253, 17
	v_readlane_b32 s55, v253, 18
	v_readlane_b32 s56, v253, 19
	v_readlane_b32 s57, v253, 20
	v_readlane_b32 s58, v253, 21
	v_readlane_b32 s59, v253, 22
	v_readlane_b32 s60, v253, 23
	v_readlane_b32 s65, v253, 28
	v_readlane_b32 s66, v253, 29
	v_readlane_b32 s67, v253, 30
	s_waitcnt vmcnt(0)
	v_add_f32_e32 v48, 1.0, v42
	v_add_f32_e32 v49, 1.0, v43
	v_add_f32_e32 v42, 1.0, v44
	v_add_f32_e32 v43, 1.0, v45
	v_mul_f32_e32 v45, v55, v49
	v_mul_f32_e32 v44, v54, v48
	global_load_dwordx4 v[46:49], v[46:47], off offset:3072
	v_mul_f32_e32 v43, v57, v43
	v_mul_f32_e32 v42, v56, v42
.LBB0_33:
	v_add_u32_e32 v50, -3, v122
	v_ashrrev_i32_e32 v51, 31, v50
	v_lshlrev_b64 v[162:163], 12, v[50:51]
	v_lshl_add_u64 v[52:53], v[114:115], 0, v[162:163]
	v_lshlrev_b64 v[160:161], 11, v[50:51]
	v_lshl_add_u64 v[50:51], v[116:117], 0, v[160:161]
	global_load_dwordx4 v[110:113], v[52:53], off
	global_load_dwordx2 v[170:171], v[50:51], off
	global_load_dwordx4 v[106:109], v[52:53], off offset:1024
	global_load_dwordx2 v[168:169], v[50:51], off offset:512
	global_load_dwordx4 v[102:105], v[52:53], off offset:2048
	global_load_dwordx2 v[166:167], v[50:51], off offset:1024
	global_load_dwordx4 v[98:101], v[52:53], off offset:3072
	global_load_dwordx2 v[164:165], v[50:51], off offset:1536
	v_ashrrev_i32_e32 v123, 31, v122
	v_lshlrev_b64 v[126:127], 12, v[122:123]
	v_lshlrev_b64 v[124:125], 11, v[122:123]
	v_add_u32_e32 v50, -2, v122
	v_ashrrev_i32_e32 v51, 31, v50
	v_lshlrev_b64 v[150:151], 12, v[50:51]
	v_lshl_add_u64 v[52:53], v[114:115], 0, v[150:151]
	v_lshlrev_b64 v[140:141], 11, v[50:51]
	v_lshl_add_u64 v[50:51], v[116:117], 0, v[140:141]
	global_load_dwordx4 v[94:97], v[52:53], off
	global_load_dwordx2 v[158:159], v[50:51], off
	global_load_dwordx4 v[90:93], v[52:53], off offset:1024
	global_load_dwordx2 v[156:157], v[50:51], off offset:512
	global_load_dwordx4 v[86:89], v[52:53], off offset:2048
	global_load_dwordx2 v[154:155], v[50:51], off offset:1024
	global_load_dwordx4 v[82:85], v[52:53], off offset:3072
	global_load_dwordx2 v[152:153], v[50:51], off offset:1536
	v_add_u32_e32 v50, -1, v122
	v_ashrrev_i32_e32 v51, 31, v50
	v_lshlrev_b64 v[138:139], 12, v[50:51]
	v_lshlrev_b64 v[136:137], 11, v[50:51]
	v_lshl_add_u64 v[52:53], v[114:115], 0, v[138:139]
	v_lshl_add_u64 v[50:51], v[116:117], 0, v[136:137]
	global_load_dwordx4 v[78:81], v[52:53], off
	global_load_dwordx2 v[148:149], v[50:51], off
	global_load_dwordx4 v[74:77], v[52:53], off offset:1024
	global_load_dwordx2 v[146:147], v[50:51], off offset:512
	global_load_dwordx4 v[70:73], v[52:53], off offset:2048
	global_load_dwordx2 v[144:145], v[50:51], off offset:1024
	global_load_dwordx4 v[66:69], v[52:53], off offset:3072
	global_load_dwordx2 v[142:143], v[50:51], off offset:1536
	v_lshl_add_u64 v[50:51], v[114:115], 0, v[126:127]
	v_lshl_add_u64 v[128:129], v[116:117], 0, v[124:125]
	v_lshl_add_u64 v[162:163], v[120:121], 0, v[162:163]
	global_load_dwordx4 v[62:65], v[50:51], off
	global_load_dwordx2 v[134:135], v[128:129], off
	global_load_dwordx4 v[58:61], v[50:51], off offset:1024
	global_load_dwordx2 v[132:133], v[128:129], off offset:512
	global_load_dwordx4 v[54:57], v[50:51], off offset:2048
	global_load_dwordx2 v[130:131], v[128:129], off offset:1024
	s_nop 0
	global_load_dwordx4 v[50:53], v[50:51], off offset:3072
	s_nop 0
	global_load_dwordx2 v[128:129], v[128:129], off offset:1536
	v_lshl_add_u64 v[160:161], v[118:119], 0, v[160:161]
	v_add_u32_e32 v172, s3, v172
	v_add_u32_e32 v122, s3, v122
	s_waitcnt vmcnt(30)
	v_and_b32_e32 v177, 0xffff0000, v170
	v_and_b32_e32 v179, 0xffff0000, v171
	v_lshlrev_b32_e32 v176, 16, v170
	v_lshlrev_b32_e32 v178, 16, v171
	v_mul_f32_e32 v0, v177, v177
	v_mul_f32_e32 v123, v179, v179
	v_fmac_f32_e32 v0, v176, v176
	v_fmac_f32_e32 v123, v178, v178
	s_waitcnt vmcnt(28)
	v_and_b32_e32 v173, 0xffff0000, v168
	v_and_b32_e32 v175, 0xffff0000, v169
	v_add_f32_e32 v0, v0, v123
	v_lshlrev_b32_e32 v171, 16, v168
	v_lshlrev_b32_e32 v174, 16, v169
	v_mul_f32_e32 v123, v173, v173
	v_mul_f32_e32 v168, v175, v175
	v_fmac_f32_e32 v123, v171, v171
	v_fmac_f32_e32 v168, v174, v174
	v_add_f32_e32 v123, v123, v168
	s_waitcnt vmcnt(26)
	v_and_b32_e32 v169, 0xffff0000, v166
	v_lshlrev_b32_e32 v170, 16, v167
	v_and_b32_e32 v167, 0xffff0000, v167
	v_add_f32_e32 v0, v0, v123
	v_lshlrev_b32_e32 v168, 16, v166
	v_mul_f32_e32 v123, v169, v169
	v_mul_f32_e32 v166, v167, v167
	v_fmac_f32_e32 v123, v168, v168
	v_fmac_f32_e32 v166, v170, v170
	v_add_f32_e32 v123, v123, v166
	v_add_f32_e32 v166, v0, v123
	s_waitcnt vmcnt(24)
	v_lshlrev_b32_e32 v0, 16, v164
	v_and_b32_e32 v123, 0xffff0000, v164
	v_lshlrev_b32_e32 v164, 16, v165
	v_and_b32_e32 v165, 0xffff0000, v165
	v_mul_f32_e32 v180, v123, v123
	v_mul_f32_e32 v181, v165, v165
	v_fmac_f32_e32 v180, v0, v0
	v_fmac_f32_e32 v181, v164, v164
	v_add_f32_e32 v180, v180, v181
	v_add_f32_e32 v166, v166, v180
	s_nop 1
	v_add_f32_dpp v166, v166, v166 quad_perm:[1,0,3,2] row_mask:0xf bank_mask:0xf bound_ctrl:1
	s_nop 1
	v_add_f32_dpp v166, v166, v166 quad_perm:[2,3,0,1] row_mask:0xf bank_mask:0xf bound_ctrl:1
	s_nop 1
	v_add_f32_dpp v166, v166, v166 row_half_mirror row_mask:0xf bank_mask:0xf bound_ctrl:1
	s_nop 1
	v_add_f32_dpp v166, v166, v166 row_mirror row_mask:0xf bank_mask:0xf bound_ctrl:1
	s_nop 0
	v_readlane_b32 s1, v166, 16
	v_readlane_b32 s6, v166, 48
	v_readlane_b32 s0, v166, 0
	v_readlane_b32 s2, v166, 32
	v_mov_b32_e32 v166, s1
	v_mov_b32_e32 v180, s6
	v_add_f32_e32 v166, s0, v166
	v_add_f32_e32 v180, s2, v180
	v_add_f32_e32 v166, v166, v180
	v_fmamk_f32 v166, v166, 0x3a800000, v188
	v_cmp_gt_f32_e32 vcc, s49, v166
	v_mul_f32_e32 v180, 0x4f800000, v166
	s_nop 0
	v_cndmask_b32_e32 v166, v166, v180, vcc
	v_sqrt_f32_e32 v180, v166
	s_nop 0
	v_add_u32_e32 v181, -1, v180
	v_fma_f32 v182, -v181, v180, v166
	v_cmp_ge_f32_e64 s[0:1], 0, v182
	v_add_u32_e32 v182, 1, v180
	s_nop 0
	v_cndmask_b32_e64 v181, v180, v181, s[0:1]
	v_fma_f32 v180, -v182, v180, v166
	v_cmp_lt_f32_e64 s[0:1], 0, v180
	s_nop 1
	v_cndmask_b32_e64 v180, v181, v182, s[0:1]
	v_mul_f32_e32 v181, 0x37800000, v180
	v_cndmask_b32_e32 v180, v180, v181, vcc
	v_cmp_class_f32_e32 vcc, v166, v189
	s_nop 1
	v_cndmask_b32_e32 v166, v180, v166, vcc
	v_div_scale_f32 v180, s[0:1], v166, v166, 1.0
	v_rcp_f32_e32 v181, v180
	s_nop 0
	v_fma_f32 v182, -v180, v181, 1.0
	v_fmac_f32_e32 v181, v182, v181
	v_div_scale_f32 v182, vcc, 1.0, v166, 1.0
	v_mul_f32_e32 v183, v182, v181
	v_fma_f32 v184, -v180, v183, v182
	v_fmac_f32_e32 v183, v184, v181
	v_fma_f32 v180, -v180, v183, v182
	v_div_fmas_f32 v180, v180, v181, v183
	v_div_fixup_f32 v166, v180, v166, 1.0
	v_mul_f32_e32 v177, v177, v166
	v_mul_f32_e32 v179, v179, v166
	v_mul_f32_e32 v173, v173, v166
	v_mul_f32_e32 v175, v175, v166
	v_mul_f32_e32 v176, v176, v166
	v_mul_f32_e32 v178, v178, v166
	v_fma_f32 v113, v3, v179, v113
	v_fma_f32 v111, v5, v177, v111
	v_mul_f32_e32 v171, v171, v166
	v_mul_f32_e32 v174, v174, v166
	v_fma_f32 v109, v15, v175, v109
	v_fma_f32 v107, v17, v173, v107
	v_mul_f32_e32 v169, v169, v166
	v_mul_f32_e32 v167, v167, v166
	v_fma_f32 v112, v2, v178, v112
	v_fmac_f32_e32 v110, v4, v176
	v_mul_f32_e32 v176, v111, v111
	v_mul_f32_e32 v177, v113, v113
	v_fma_f32 v108, v14, v174, v108
	v_fmac_f32_e32 v106, v16, v171
	v_mul_f32_e32 v171, v107, v107
	v_mul_f32_e32 v173, v109, v109
	v_mul_f32_e32 v168, v168, v166
	v_mul_f32_e32 v170, v170, v166
	v_fma_f32 v105, v27, v167, v105
	v_fma_f32 v103, v29, v169, v103
	v_mul_f32_e32 v123, v123, v166
	v_mul_f32_e32 v165, v165, v166
	v_fmac_f32_e32 v176, v110, v110
	v_fmac_f32_e32 v177, v112, v112
	v_fmac_f32_e32 v171, v106, v106
	v_fmac_f32_e32 v173, v108, v108
	v_fma_f32 v104, v26, v170, v104
	v_fmac_f32_e32 v102, v28, v168
	v_mul_f32_e32 v167, v103, v103
	v_mul_f32_e32 v168, v105, v105
	v_mul_f32_e32 v0, v0, v166
	v_mul_f32_e32 v164, v164, v166
	v_fma_f32 v101, v39, v165, v101
	v_fma_f32 v99, v41, v123, v99
	v_add_f32_e32 v176, v176, v177
	v_add_f32_e32 v171, v171, v173
	v_fmac_f32_e32 v167, v102, v102
	v_fmac_f32_e32 v168, v104, v104
	v_fma_f32 v100, v38, v164, v100
	v_fmac_f32_e32 v98, v40, v0
	v_mul_f32_e32 v0, v99, v99
	v_mul_f32_e32 v123, v101, v101
	v_add_f32_e32 v171, v176, v171
	v_add_f32_e32 v167, v167, v168
	v_fmac_f32_e32 v0, v98, v98
	v_fmac_f32_e32 v123, v100, v100
	v_add_f32_e32 v167, v167, v171
	v_add_f32_e32 v0, v0, v123
	v_add_f32_e32 v0, v0, v167
	s_nop 1
	s_nop 1
	v_add_f32_dpp v0, v0, v0 quad_perm:[1,0,3,2] row_mask:0xf bank_mask:0xf bound_ctrl:1
	s_nop 1
	s_nop 1
	v_add_f32_dpp v0, v0, v0 quad_perm:[2,3,0,1] row_mask:0xf bank_mask:0xf bound_ctrl:1
	s_nop 1
	v_add_f32_dpp v0, v0, v0 row_half_mirror row_mask:0xf bank_mask:0xf bound_ctrl:1
	s_nop 1
	v_add_f32_dpp v0, v0, v0 row_mirror row_mask:0xf bank_mask:0xf bound_ctrl:1
	s_nop 0
	v_readlane_b32 s1, v0, 16
	v_readlane_b32 s6, v0, 48
	v_readlane_b32 s0, v0, 0
	v_readlane_b32 s2, v0, 32
	v_mov_b32_e32 v0, s1
	v_mov_b32_e32 v123, s6
	v_add_f32_e32 v0, s0, v0
	v_add_f32_e32 v123, s2, v123
	v_add_f32_e32 v0, v0, v123
	v_fmamk_f32 v0, v0, 0x3a800000, v188
	v_cmp_gt_f32_e32 vcc, s49, v0
	v_mul_f32_e32 v123, 0x4f800000, v0
	s_nop 0
	v_cndmask_b32_e32 v0, v0, v123, vcc
	v_sqrt_f32_e32 v123, v0
	s_nop 0
	v_add_u32_e32 v162, -1, v123
	v_fma_f32 v163, -v162, v123, v0
	v_cmp_ge_f32_e64 s[0:1], 0, v163
	v_add_u32_e32 v163, 1, v123
	s_nop 0
	v_cndmask_b32_e64 v162, v123, v162, s[0:1]
	v_fma_f32 v123, -v163, v123, v0
	v_cmp_lt_f32_e64 s[0:1], 0, v123
	s_nop 1
	v_cndmask_b32_e64 v123, v162, v163, s[0:1]
	v_mul_f32_e32 v162, 0x37800000, v123
	v_cndmask_b32_e32 v123, v123, v162, vcc
	v_cmp_class_f32_e32 vcc, v0, v189
	s_nop 1
	v_cndmask_b32_e32 v0, v123, v0, vcc
	v_div_scale_f32 v123, s[0:1], v0, v0, 1.0
	v_rcp_f32_e32 v162, v123
	s_nop 0
	v_fma_f32 v163, -v123, v162, 1.0
	v_fmac_f32_e32 v162, v163, v162
	v_div_scale_f32 v163, vcc, 1.0, v0, 1.0
	v_mul_f32_e32 v164, v163, v162
	v_fma_f32 v165, -v123, v164, v163
	v_fmac_f32_e32 v164, v165, v162
	v_fma_f32 v123, -v123, v164, v163
	v_div_fmas_f32 v123, v123, v162, v164
	v_div_fixup_f32 v0, v123, v0, 1.0
	v_mul_f32_e32 v111, v111, v0
	v_mul_f32_e32 v110, v110, v0
	v_mul_f32_e32 v107, v107, v0
	v_mul_f32_e32 v106, v106, v0
	v_mul_f32_e32 v103, v103, v0
	v_mul_f32_e32 v102, v102, v0
	v_mul_f32_e32 v98, v98, v0
	v_mul_f32_e32 v113, v113, v0
	v_mul_f32_e32 v112, v112, v0
	v_fma_f32 v110, v8, v110, v10
	v_fma_f32 v111, v9, v111, v11
	v_mul_f32_e32 v109, v109, v0
	v_mul_f32_e32 v108, v108, v0
	v_fma_f32 v106, v20, v106, v22
	v_fma_f32 v107, v21, v107, v23
	v_mul_f32_e32 v105, v105, v0
	v_mul_f32_e32 v104, v104, v0
	v_fma_f32 v102, v32, v102, v34
	v_fma_f32 v103, v33, v103, v35
	v_mul_f32_e32 v99, v99, v0
	v_mul_f32_e32 v101, v101, v0
	v_fma_f32 v98, v44, v98, v46
	v_fma_f32 v112, v6, v112, v12
	v_fma_f32 v113, v7, v113, v13
	v_cvt_pk_bf16_f32 v110, v110, v111
	v_cvt_pk_bf16_f32 v111, v112, v113
	global_store_dwordx2 v[160:161], v[110:111], off
	v_fma_f32 v108, v18, v108, v24
	v_fma_f32 v109, v19, v109, v25
	v_cvt_pk_bf16_f32 v106, v106, v107
	v_cvt_pk_bf16_f32 v107, v108, v109
	global_store_dwordx2 v[160:161], v[106:107], off offset:512
	v_fma_f32 v104, v30, v104, v36
	v_fma_f32 v105, v31, v105, v37
	v_cvt_pk_bf16_f32 v102, v102, v103
	v_cvt_pk_bf16_f32 v103, v104, v105
	global_store_dwordx2 v[160:161], v[102:103], off offset:1024
	v_mul_f32_e32 v0, v100, v0
	v_fma_f32 v100, v43, v101, v49
	v_fma_f32 v99, v45, v99, v47
	v_cvt_pk_bf16_f32 v98, v98, v99
	v_fma_f32 v0, v42, v0, v48
	v_cvt_pk_bf16_f32 v99, v0, v100
	global_store_dwordx2 v[160:161], v[98:99], off offset:1536
	s_waitcnt vmcnt(26)
	v_and_b32_e32 v98, 0xffff0000, v158
	v_and_b32_e32 v100, 0xffff0000, v159
	v_lshlrev_b32_e32 v0, 16, v158
	v_lshlrev_b32_e32 v99, 16, v159
	v_mul_f32_e32 v101, v98, v98
	v_mul_f32_e32 v102, v100, v100
	v_fmac_f32_e32 v101, v0, v0
	v_fmac_f32_e32 v102, v99, v99
	s_waitcnt vmcnt(24)
	v_and_b32_e32 v103, 0xffff0000, v156
	v_and_b32_e32 v105, 0xffff0000, v157
	v_add_f32_e32 v101, v101, v102
	v_lshlrev_b32_e32 v102, 16, v156
	v_lshlrev_b32_e32 v104, 16, v157
	v_mul_f32_e32 v106, v103, v103
	v_mul_f32_e32 v107, v105, v105
	v_fmac_f32_e32 v106, v102, v102
	v_fmac_f32_e32 v107, v104, v104
	v_add_f32_e32 v106, v106, v107
	s_waitcnt vmcnt(22)
	v_and_b32_e32 v107, 0xffff0000, v154
	v_and_b32_e32 v109, 0xffff0000, v155
	v_add_f32_e32 v101, v101, v106
	v_lshlrev_b32_e32 v106, 16, v154
	v_lshlrev_b32_e32 v108, 16, v155
	v_mul_f32_e32 v110, v107, v107
	v_mul_f32_e32 v111, v109, v109
	v_fmac_f32_e32 v110, v106, v106
	v_fmac_f32_e32 v111, v108, v108
	v_add_f32_e32 v110, v110, v111
	s_waitcnt vmcnt(20)
	v_and_b32_e32 v111, 0xffff0000, v152
	v_and_b32_e32 v113, 0xffff0000, v153
	v_add_f32_e32 v101, v101, v110
	v_lshlrev_b32_e32 v110, 16, v152
	v_lshlrev_b32_e32 v112, 16, v153
	v_mul_f32_e32 v123, v111, v111
	v_mul_f32_e32 v152, v113, v113
	v_fmac_f32_e32 v123, v110, v110
	v_fmac_f32_e32 v152, v112, v112
	v_add_f32_e32 v123, v123, v152
	v_add_f32_e32 v101, v101, v123
	s_nop 1
	v_add_f32_dpp v101, v101, v101 quad_perm:[1,0,3,2] row_mask:0xf bank_mask:0xf bound_ctrl:1
	s_nop 1
	v_add_f32_dpp v101, v101, v101 quad_perm:[2,3,0,1] row_mask:0xf bank_mask:0xf bound_ctrl:1
	s_nop 1
	v_add_f32_dpp v101, v101, v101 row_half_mirror row_mask:0xf bank_mask:0xf bound_ctrl:1
	s_nop 1
	v_add_f32_dpp v101, v101, v101 row_mirror row_mask:0xf bank_mask:0xf bound_ctrl:1
	s_nop 0
	v_readlane_b32 s1, v101, 16
	v_readlane_b32 s6, v101, 48
	v_readlane_b32 s0, v101, 0
	v_readlane_b32 s2, v101, 32
	v_mov_b32_e32 v101, s1
	v_mov_b32_e32 v123, s6
	v_add_f32_e32 v101, s0, v101
	v_add_f32_e32 v123, s2, v123
	v_add_f32_e32 v101, v101, v123
	v_fmamk_f32 v101, v101, 0x3a800000, v188
	v_cmp_gt_f32_e32 vcc, s49, v101
	v_mul_f32_e32 v123, 0x4f800000, v101
	s_nop 0
	v_cndmask_b32_e32 v101, v101, v123, vcc
	v_sqrt_f32_e32 v123, v101
	s_nop 0
	v_add_u32_e32 v152, -1, v123
	v_fma_f32 v153, -v152, v123, v101
	v_cmp_ge_f32_e64 s[0:1], 0, v153
	v_add_u32_e32 v153, 1, v123
	s_nop 0
	v_cndmask_b32_e64 v152, v123, v152, s[0:1]
	v_fma_f32 v123, -v153, v123, v101
	v_cmp_lt_f32_e64 s[0:1], 0, v123
	s_nop 1
	v_cndmask_b32_e64 v123, v152, v153, s[0:1]
	v_mul_f32_e32 v152, 0x37800000, v123
	v_cndmask_b32_e32 v123, v123, v152, vcc
	v_cmp_class_f32_e32 vcc, v101, v189
	s_nop 1
	v_cndmask_b32_e32 v101, v123, v101, vcc
	v_div_scale_f32 v123, s[0:1], v101, v101, 1.0
	v_rcp_f32_e32 v152, v123
	s_nop 0
	v_fma_f32 v153, -v123, v152, 1.0
	v_fmac_f32_e32 v152, v153, v152
	v_div_scale_f32 v153, vcc, 1.0, v101, 1.0
	v_mul_f32_e32 v154, v153, v152
	v_fma_f32 v155, -v123, v154, v153
	v_fmac_f32_e32 v154, v155, v152
	v_fma_f32 v123, -v123, v154, v153
	v_div_fmas_f32 v123, v123, v152, v154
	v_div_fixup_f32 v101, v123, v101, 1.0
	v_mul_f32_e32 v98, v98, v101
	v_mul_f32_e32 v100, v100, v101
	v_mul_f32_e32 v0, v0, v101
	v_mul_f32_e32 v99, v99, v101
	v_fma_f32 v97, v3, v100, v97
	v_fma_f32 v95, v5, v98, v95
	v_fma_f32 v96, v2, v99, v96
	v_fmac_f32_e32 v94, v4, v0
	v_mul_f32_e32 v0, v95, v95
	v_mul_f32_e32 v100, v97, v97
	v_fmac_f32_e32 v0, v94, v94
	v_fmac_f32_e32 v100, v96, v96
	v_add_f32_e32 v0, v0, v100
	v_mul_f32_e32 v100, v102, v101
	v_mul_f32_e32 v102, v103, v101
	v_mul_f32_e32 v103, v104, v101
	v_mul_f32_e32 v104, v105, v101
	v_fma_f32 v93, v15, v104, v93
	v_fma_f32 v91, v17, v102, v91
	v_fma_f32 v92, v14, v103, v92
	v_fmac_f32_e32 v90, v16, v100
	v_mul_f32_e32 v100, v91, v91
	v_mul_f32_e32 v102, v93, v93
	v_fmac_f32_e32 v100, v90, v90
	v_fmac_f32_e32 v102, v92, v92
	v_add_f32_e32 v100, v100, v102
	v_mul_f32_e32 v102, v107, v101
	v_mul_f32_e32 v104, v109, v101
	v_add_f32_e32 v0, v0, v100
	v_mul_f32_e32 v100, v106, v101
	v_mul_f32_e32 v103, v108, v101
	v_fma_f32 v89, v27, v104, v89
	v_fma_f32 v87, v29, v102, v87
	v_fma_f32 v88, v26, v103, v88
	v_fmac_f32_e32 v86, v28, v100
	v_mul_f32_e32 v100, v87, v87
	v_mul_f32_e32 v102, v89, v89
	v_fmac_f32_e32 v100, v86, v86
	v_fmac_f32_e32 v102, v88, v88
	v_add_f32_e32 v100, v100, v102
	v_add_f32_e32 v0, v100, v0
	v_mul_f32_e32 v100, v110, v101
	v_mul_f32_e32 v102, v111, v101
	v_mul_f32_e32 v103, v112, v101
	v_mul_f32_e32 v101, v113, v101
	v_lshl_add_u64 v[98:99], v[120:121], 0, v[150:151]
	v_fma_f32 v85, v39, v101, v85
	v_fma_f32 v84, v38, v103, v84
	v_fma_f32 v83, v41, v102, v83
	v_fmac_f32_e32 v82, v40, v100
	s_nop 1
	s_nop 1
	s_nop 1
	s_nop 1
	v_mul_f32_e32 v98, v83, v83
	v_mul_f32_e32 v99, v85, v85
	v_fmac_f32_e32 v98, v82, v82
	v_fmac_f32_e32 v99, v84, v84
	v_add_f32_e32 v98, v98, v99
	v_add_f32_e32 v0, v98, v0
	s_nop 1
	v_add_f32_dpp v0, v0, v0 quad_perm:[1,0,3,2] row_mask:0xf bank_mask:0xf bound_ctrl:1
	s_nop 1
	v_add_f32_dpp v0, v0, v0 quad_perm:[2,3,0,1] row_mask:0xf bank_mask:0xf bound_ctrl:1
	s_nop 1
	v_add_f32_dpp v0, v0, v0 row_half_mirror row_mask:0xf bank_mask:0xf bound_ctrl:1
	s_nop 1
	v_add_f32_dpp v0, v0, v0 row_mirror row_mask:0xf bank_mask:0xf bound_ctrl:1
	s_nop 0
	v_readlane_b32 s1, v0, 16
	v_readlane_b32 s6, v0, 48
	v_readlane_b32 s0, v0, 0
	v_readlane_b32 s2, v0, 32
	v_mov_b32_e32 v0, s1
	v_mov_b32_e32 v98, s6
	v_add_f32_e32 v0, s0, v0
	v_add_f32_e32 v98, s2, v98
	v_add_f32_e32 v0, v0, v98
	v_fmamk_f32 v0, v0, 0x3a800000, v188
	v_cmp_gt_f32_e32 vcc, s49, v0
	v_mul_f32_e32 v98, 0x4f800000, v0
	s_nop 0
	v_cndmask_b32_e32 v0, v0, v98, vcc
	v_sqrt_f32_e32 v98, v0
	s_nop 0
	v_add_u32_e32 v99, -1, v98
	v_fma_f32 v100, -v99, v98, v0
	v_cmp_ge_f32_e64 s[0:1], 0, v100
	v_add_u32_e32 v100, 1, v98
	s_nop 0
	v_cndmask_b32_e64 v99, v98, v99, s[0:1]
	v_fma_f32 v98, -v100, v98, v0
	v_cmp_lt_f32_e64 s[0:1], 0, v98
	s_nop 1
	v_cndmask_b32_e64 v98, v99, v100, s[0:1]
	v_mul_f32_e32 v99, 0x37800000, v98
	v_cndmask_b32_e32 v98, v98, v99, vcc
	v_cmp_class_f32_e32 vcc, v0, v189
	s_nop 1
	v_cndmask_b32_e32 v0, v98, v0, vcc
	v_div_scale_f32 v98, s[0:1], v0, v0, 1.0
	v_rcp_f32_e32 v99, v98
	s_nop 0
	v_fma_f32 v100, -v98, v99, 1.0
	v_fmac_f32_e32 v99, v100, v99
	v_div_scale_f32 v100, vcc, 1.0, v0, 1.0
	v_mul_f32_e32 v101, v100, v99
	v_fma_f32 v102, -v98, v101, v100
	v_fmac_f32_e32 v101, v102, v99
	v_fma_f32 v98, -v98, v101, v100
	v_div_fmas_f32 v98, v98, v99, v101
	v_div_fixup_f32 v0, v98, v0, 1.0
	v_mul_f32_e32 v95, v95, v0
	v_mul_f32_e32 v94, v94, v0
	v_mul_f32_e32 v91, v91, v0
	v_mul_f32_e32 v90, v90, v0
	v_mul_f32_e32 v87, v87, v0
	v_mul_f32_e32 v86, v86, v0
	v_mul_f32_e32 v82, v82, v0
	v_lshl_add_u64 v[98:99], v[118:119], 0, v[140:141]
	v_mul_f32_e32 v97, v97, v0
	v_mul_f32_e32 v96, v96, v0
	v_fma_f32 v94, v8, v94, v10
	v_fma_f32 v95, v9, v95, v11
	v_mul_f32_e32 v93, v93, v0
	v_mul_f32_e32 v92, v92, v0
	v_fma_f32 v90, v20, v90, v22
	v_fma_f32 v91, v21, v91, v23
	v_mul_f32_e32 v89, v89, v0
	v_mul_f32_e32 v88, v88, v0
	v_fma_f32 v86, v32, v86, v34
	v_fma_f32 v87, v33, v87, v35
	v_mul_f32_e32 v83, v83, v0
	v_mul_f32_e32 v85, v85, v0
	v_fma_f32 v82, v44, v82, v46
	v_fma_f32 v96, v6, v96, v12
	v_fma_f32 v97, v7, v97, v13
	v_cvt_pk_bf16_f32 v94, v94, v95
	v_cvt_pk_bf16_f32 v95, v96, v97
	global_store_dwordx2 v[98:99], v[94:95], off
	v_fma_f32 v92, v18, v92, v24
	v_fma_f32 v93, v19, v93, v25
	v_cvt_pk_bf16_f32 v90, v90, v91
	v_cvt_pk_bf16_f32 v91, v92, v93
	global_store_dwordx2 v[98:99], v[90:91], off offset:512
	v_fma_f32 v88, v30, v88, v36
	v_fma_f32 v89, v31, v89, v37
	v_cvt_pk_bf16_f32 v86, v86, v87
	v_cvt_pk_bf16_f32 v87, v88, v89
	global_store_dwordx2 v[98:99], v[86:87], off offset:1024
	v_mul_f32_e32 v0, v84, v0
	v_fma_f32 v84, v43, v85, v49
	v_fma_f32 v83, v45, v83, v47
	v_cvt_pk_bf16_f32 v82, v82, v83
	v_fma_f32 v0, v42, v0, v48
	v_cvt_pk_bf16_f32 v83, v0, v84
	global_store_dwordx2 v[98:99], v[82:83], off offset:1536
	s_waitcnt vmcnt(22)
	v_and_b32_e32 v82, 0xffff0000, v148
	v_and_b32_e32 v84, 0xffff0000, v149
	v_lshlrev_b32_e32 v0, 16, v148
	v_lshlrev_b32_e32 v83, 16, v149
	v_mul_f32_e32 v85, v82, v82
	v_mul_f32_e32 v86, v84, v84
	v_fmac_f32_e32 v85, v0, v0
	v_fmac_f32_e32 v86, v83, v83
	s_waitcnt vmcnt(20)
	v_and_b32_e32 v87, 0xffff0000, v146
	v_and_b32_e32 v89, 0xffff0000, v147
	v_add_f32_e32 v85, v85, v86
	v_lshlrev_b32_e32 v86, 16, v146
	v_lshlrev_b32_e32 v88, 16, v147
	v_mul_f32_e32 v90, v87, v87
	v_mul_f32_e32 v91, v89, v89
	v_fmac_f32_e32 v90, v86, v86
	v_fmac_f32_e32 v91, v88, v88
	v_add_f32_e32 v90, v90, v91
	s_waitcnt vmcnt(18)
	v_and_b32_e32 v91, 0xffff0000, v144
	v_and_b32_e32 v93, 0xffff0000, v145
	v_add_f32_e32 v85, v85, v90
	v_lshlrev_b32_e32 v90, 16, v144
	v_lshlrev_b32_e32 v92, 16, v145
	v_mul_f32_e32 v94, v91, v91
	v_mul_f32_e32 v95, v93, v93
	v_fmac_f32_e32 v94, v90, v90
	v_fmac_f32_e32 v95, v92, v92
	v_add_f32_e32 v94, v94, v95
	s_waitcnt vmcnt(16)
	v_and_b32_e32 v95, 0xffff0000, v142
	v_and_b32_e32 v97, 0xffff0000, v143
	v_add_f32_e32 v85, v85, v94
	v_lshlrev_b32_e32 v94, 16, v142
	v_lshlrev_b32_e32 v96, 16, v143
	v_mul_f32_e32 v98, v95, v95
	v_mul_f32_e32 v99, v97, v97
	v_fmac_f32_e32 v98, v94, v94
	v_fmac_f32_e32 v99, v96, v96
	v_add_f32_e32 v98, v98, v99
	v_add_f32_e32 v85, v85, v98
	s_nop 1
	v_add_f32_dpp v85, v85, v85 quad_perm:[1,0,3,2] row_mask:0xf bank_mask:0xf bound_ctrl:1
	s_nop 1
	v_add_f32_dpp v85, v85, v85 quad_perm:[2,3,0,1] row_mask:0xf bank_mask:0xf bound_ctrl:1
	s_nop 1
	v_add_f32_dpp v85, v85, v85 row_half_mirror row_mask:0xf bank_mask:0xf bound_ctrl:1
	s_nop 1
	v_add_f32_dpp v85, v85, v85 row_mirror row_mask:0xf bank_mask:0xf bound_ctrl:1
	s_nop 0
	v_readlane_b32 s1, v85, 16
	v_readlane_b32 s6, v85, 48
	v_readlane_b32 s0, v85, 0
	v_readlane_b32 s2, v85, 32
	v_mov_b32_e32 v85, s1
	v_mov_b32_e32 v98, s6
	v_add_f32_e32 v85, s0, v85
	v_add_f32_e32 v98, s2, v98
	v_add_f32_e32 v85, v85, v98
	v_fmamk_f32 v85, v85, 0x3a800000, v188
	v_cmp_gt_f32_e32 vcc, s49, v85
	v_mul_f32_e32 v98, 0x4f800000, v85
	s_nop 0
	v_cndmask_b32_e32 v85, v85, v98, vcc
	v_sqrt_f32_e32 v98, v85
	s_nop 0
	v_add_u32_e32 v99, -1, v98
	v_fma_f32 v100, -v99, v98, v85
	v_cmp_ge_f32_e64 s[0:1], 0, v100
	v_add_u32_e32 v100, 1, v98
	s_nop 0
	v_cndmask_b32_e64 v99, v98, v99, s[0:1]
	v_fma_f32 v98, -v100, v98, v85
	v_cmp_lt_f32_e64 s[0:1], 0, v98
	s_nop 1
	v_cndmask_b32_e64 v98, v99, v100, s[0:1]
	v_mul_f32_e32 v99, 0x37800000, v98
	v_cndmask_b32_e32 v98, v98, v99, vcc
	v_cmp_class_f32_e32 vcc, v85, v189
	s_nop 1
	v_cndmask_b32_e32 v85, v98, v85, vcc
	v_div_scale_f32 v98, s[0:1], v85, v85, 1.0
	v_rcp_f32_e32 v99, v98
	s_nop 0
	v_fma_f32 v100, -v98, v99, 1.0
	v_fmac_f32_e32 v99, v100, v99
	v_div_scale_f32 v100, vcc, 1.0, v85, 1.0
	v_mul_f32_e32 v101, v100, v99
	v_fma_f32 v102, -v98, v101, v100
	v_fmac_f32_e32 v101, v102, v99
	v_fma_f32 v98, -v98, v101, v100
	v_div_fmas_f32 v98, v98, v99, v101
	v_div_fixup_f32 v85, v98, v85, 1.0
	v_mul_f32_e32 v82, v82, v85
	v_mul_f32_e32 v84, v84, v85
	v_mul_f32_e32 v0, v0, v85
	v_mul_f32_e32 v83, v83, v85
	v_fma_f32 v81, v3, v84, v81
	v_fma_f32 v79, v5, v82, v79
	v_fma_f32 v80, v2, v83, v80
	v_fmac_f32_e32 v78, v4, v0
	v_mul_f32_e32 v0, v79, v79
	v_mul_f32_e32 v84, v81, v81
	v_fmac_f32_e32 v0, v78, v78
	v_fmac_f32_e32 v84, v80, v80
	v_add_f32_e32 v0, v0, v84
	v_mul_f32_e32 v84, v86, v85
	v_mul_f32_e32 v86, v87, v85
	v_mul_f32_e32 v87, v88, v85
	v_mul_f32_e32 v88, v89, v85
	v_fma_f32 v77, v15, v88, v77
	v_fma_f32 v75, v17, v86, v75
	v_fma_f32 v76, v14, v87, v76
	v_fmac_f32_e32 v74, v16, v84
	v_mul_f32_e32 v84, v75, v75
	v_mul_f32_e32 v86, v77, v77
	v_fmac_f32_e32 v84, v74, v74
	v_fmac_f32_e32 v86, v76, v76
	v_add_f32_e32 v84, v84, v86
	v_mul_f32_e32 v86, v91, v85
	v_mul_f32_e32 v88, v93, v85
	v_add_f32_e32 v0, v0, v84
	v_mul_f32_e32 v84, v90, v85
	v_mul_f32_e32 v87, v92, v85
	v_fma_f32 v73, v27, v88, v73
	v_fma_f32 v71, v29, v86, v71
	v_fma_f32 v72, v26, v87, v72
	v_fmac_f32_e32 v70, v28, v84
	v_mul_f32_e32 v84, v71, v71
	v_mul_f32_e32 v86, v73, v73
	v_fmac_f32_e32 v84, v70, v70
	v_fmac_f32_e32 v86, v72, v72
	v_add_f32_e32 v84, v84, v86
	v_add_f32_e32 v0, v84, v0
	v_mul_f32_e32 v84, v94, v85
	v_mul_f32_e32 v86, v95, v85
	v_mul_f32_e32 v87, v96, v85
	v_mul_f32_e32 v85, v97, v85
	v_lshl_add_u64 v[82:83], v[120:121], 0, v[138:139]
	v_fma_f32 v69, v39, v85, v69
	v_fma_f32 v68, v38, v87, v68
	v_fma_f32 v67, v41, v86, v67
	v_fmac_f32_e32 v66, v40, v84
	s_nop 1
	s_nop 1
	s_nop 1
	s_nop 1
	v_mul_f32_e32 v82, v67, v67
	v_mul_f32_e32 v83, v69, v69
	v_fmac_f32_e32 v82, v66, v66
	v_fmac_f32_e32 v83, v68, v68
	v_add_f32_e32 v82, v82, v83
	v_add_f32_e32 v0, v82, v0
	s_nop 1
	v_add_f32_dpp v0, v0, v0 quad_perm:[1,0,3,2] row_mask:0xf bank_mask:0xf bound_ctrl:1
	s_nop 1
	v_add_f32_dpp v0, v0, v0 quad_perm:[2,3,0,1] row_mask:0xf bank_mask:0xf bound_ctrl:1
	s_nop 1
	v_add_f32_dpp v0, v0, v0 row_half_mirror row_mask:0xf bank_mask:0xf bound_ctrl:1
	s_nop 1
	v_add_f32_dpp v0, v0, v0 row_mirror row_mask:0xf bank_mask:0xf bound_ctrl:1
	s_nop 0
	v_readlane_b32 s1, v0, 16
	v_readlane_b32 s6, v0, 48
	v_readlane_b32 s0, v0, 0
	v_readlane_b32 s2, v0, 32
	v_mov_b32_e32 v0, s1
	v_mov_b32_e32 v82, s6
	v_add_f32_e32 v0, s0, v0
	v_add_f32_e32 v82, s2, v82
	v_add_f32_e32 v0, v0, v82
	v_fmamk_f32 v0, v0, 0x3a800000, v188
	v_cmp_gt_f32_e32 vcc, s49, v0
	v_mul_f32_e32 v82, 0x4f800000, v0
	s_nop 0
	v_cndmask_b32_e32 v0, v0, v82, vcc
	v_sqrt_f32_e32 v82, v0
	s_nop 0
	v_add_u32_e32 v83, -1, v82
	v_fma_f32 v84, -v83, v82, v0
	v_cmp_ge_f32_e64 s[0:1], 0, v84
	v_add_u32_e32 v84, 1, v82
	s_nop 0
	v_cndmask_b32_e64 v83, v82, v83, s[0:1]
	v_fma_f32 v82, -v84, v82, v0
	v_cmp_lt_f32_e64 s[0:1], 0, v82
	s_nop 1
	v_cndmask_b32_e64 v82, v83, v84, s[0:1]
	v_mul_f32_e32 v83, 0x37800000, v82
	v_cndmask_b32_e32 v82, v82, v83, vcc
	v_cmp_class_f32_e32 vcc, v0, v189
	s_nop 1
	v_cndmask_b32_e32 v0, v82, v0, vcc
	v_div_scale_f32 v82, s[0:1], v0, v0, 1.0
	v_rcp_f32_e32 v83, v82
	s_nop 0
	v_fma_f32 v84, -v82, v83, 1.0
	v_fmac_f32_e32 v83, v84, v83
	v_div_scale_f32 v84, vcc, 1.0, v0, 1.0
	v_mul_f32_e32 v85, v84, v83
	v_fma_f32 v86, -v82, v85, v84
	v_fmac_f32_e32 v85, v86, v83
	v_fma_f32 v82, -v82, v85, v84
	v_div_fmas_f32 v82, v82, v83, v85
	v_div_fixup_f32 v0, v82, v0, 1.0
	v_mul_f32_e32 v79, v79, v0
	v_mul_f32_e32 v78, v78, v0
	v_mul_f32_e32 v75, v75, v0
	v_mul_f32_e32 v74, v74, v0
	v_mul_f32_e32 v71, v71, v0
	v_mul_f32_e32 v70, v70, v0
	v_mul_f32_e32 v66, v66, v0
	v_lshl_add_u64 v[82:83], v[118:119], 0, v[136:137]
	v_mul_f32_e32 v81, v81, v0
	v_mul_f32_e32 v80, v80, v0
	v_fma_f32 v78, v8, v78, v10
	v_fma_f32 v79, v9, v79, v11
	v_mul_f32_e32 v77, v77, v0
	v_mul_f32_e32 v76, v76, v0
	v_fma_f32 v74, v20, v74, v22
	v_fma_f32 v75, v21, v75, v23
	v_mul_f32_e32 v73, v73, v0
	v_mul_f32_e32 v72, v72, v0
	v_fma_f32 v70, v32, v70, v34
	v_fma_f32 v71, v33, v71, v35
	v_mul_f32_e32 v67, v67, v0
	v_mul_f32_e32 v69, v69, v0
	v_fma_f32 v66, v44, v66, v46
	v_fma_f32 v80, v6, v80, v12
	v_fma_f32 v81, v7, v81, v13
	v_cvt_pk_bf16_f32 v78, v78, v79
	v_cvt_pk_bf16_f32 v79, v80, v81
	global_store_dwordx2 v[82:83], v[78:79], off
	v_fma_f32 v76, v18, v76, v24
	v_fma_f32 v77, v19, v77, v25
	v_cvt_pk_bf16_f32 v74, v74, v75
	v_cvt_pk_bf16_f32 v75, v76, v77
	global_store_dwordx2 v[82:83], v[74:75], off offset:512
	v_fma_f32 v72, v30, v72, v36
	v_fma_f32 v73, v31, v73, v37
	v_cvt_pk_bf16_f32 v70, v70, v71
	v_cvt_pk_bf16_f32 v71, v72, v73
	global_store_dwordx2 v[82:83], v[70:71], off offset:1024
	v_mul_f32_e32 v0, v68, v0
	v_fma_f32 v68, v43, v69, v49
	v_fma_f32 v67, v45, v67, v47
	v_cvt_pk_bf16_f32 v66, v66, v67
	v_fma_f32 v0, v42, v0, v48
	v_cvt_pk_bf16_f32 v67, v0, v68
	global_store_dwordx2 v[82:83], v[66:67], off offset:1536
	s_waitcnt vmcnt(18)
	v_and_b32_e32 v66, 0xffff0000, v134
	v_and_b32_e32 v68, 0xffff0000, v135
	v_lshlrev_b32_e32 v0, 16, v134
	v_lshlrev_b32_e32 v67, 16, v135
	v_mul_f32_e32 v69, v66, v66
	v_mul_f32_e32 v70, v68, v68
	v_fmac_f32_e32 v69, v0, v0
	v_fmac_f32_e32 v70, v67, v67
	v_add_f32_e32 v73, v69, v70
	s_waitcnt vmcnt(16)
	v_and_b32_e32 v70, 0xffff0000, v132
	v_and_b32_e32 v72, 0xffff0000, v133
	v_lshlrev_b32_e32 v69, 16, v132
	v_lshlrev_b32_e32 v71, 16, v133
	v_mul_f32_e32 v74, v70, v70
	v_mul_f32_e32 v75, v72, v72
	v_fmac_f32_e32 v74, v69, v69
	v_fmac_f32_e32 v75, v71, v71
	v_add_f32_e32 v74, v74, v75
	v_add_f32_e32 v77, v73, v74
	s_waitcnt vmcnt(14)
	v_and_b32_e32 v74, 0xffff0000, v130
	v_and_b32_e32 v76, 0xffff0000, v131
	v_lshlrev_b32_e32 v73, 16, v130
	v_lshlrev_b32_e32 v75, 16, v131
	v_mul_f32_e32 v78, v74, v74
	v_mul_f32_e32 v79, v76, v76
	v_fmac_f32_e32 v78, v73, v73
	v_fmac_f32_e32 v79, v75, v75
	v_add_f32_e32 v78, v78, v79
	v_add_f32_e32 v81, v77, v78
	s_waitcnt vmcnt(12)
	v_and_b32_e32 v78, 0xffff0000, v128
	v_and_b32_e32 v80, 0xffff0000, v129
	v_lshlrev_b32_e32 v77, 16, v128
	v_lshlrev_b32_e32 v79, 16, v129
	v_mul_f32_e32 v82, v78, v78
	v_mul_f32_e32 v83, v80, v80
	v_fmac_f32_e32 v82, v77, v77
	v_fmac_f32_e32 v83, v79, v79
	v_add_f32_e32 v82, v82, v83
	v_add_f32_e32 v81, v81, v82
	s_nop 1
	v_add_f32_dpp v81, v81, v81 quad_perm:[1,0,3,2] row_mask:0xf bank_mask:0xf bound_ctrl:1
	s_nop 1
	v_add_f32_dpp v81, v81, v81 quad_perm:[2,3,0,1] row_mask:0xf bank_mask:0xf bound_ctrl:1
	s_nop 1
	v_add_f32_dpp v81, v81, v81 row_half_mirror row_mask:0xf bank_mask:0xf bound_ctrl:1
	s_nop 1
	v_add_f32_dpp v81, v81, v81 row_mirror row_mask:0xf bank_mask:0xf bound_ctrl:1
	s_nop 0
	v_readlane_b32 s6, v81, 16
	v_readlane_b32 s1, v81, 48
	v_readlane_b32 s2, v81, 0
	v_readlane_b32 s0, v81, 32
	v_mov_b32_e32 v81, s6
	v_mov_b32_e32 v82, s1
	v_add_f32_e32 v81, s2, v81
	v_add_f32_e32 v82, s0, v82
	v_add_f32_e32 v81, v81, v82
	v_fmamk_f32 v81, v81, 0x3a800000, v188
	v_cmp_gt_f32_e32 vcc, s49, v81
	v_mul_f32_e32 v82, 0x4f800000, v81
	s_nop 0
	v_cndmask_b32_e32 v81, v81, v82, vcc
	v_sqrt_f32_e32 v82, v81
	s_nop 0
	v_add_u32_e32 v83, -1, v82
	v_fma_f32 v84, -v83, v82, v81
	v_cmp_ge_f32_e64 s[0:1], 0, v84
	v_add_u32_e32 v84, 1, v82
	s_nop 0
	v_cndmask_b32_e64 v83, v82, v83, s[0:1]
	v_fma_f32 v82, -v84, v82, v81
	v_cmp_lt_f32_e64 s[0:1], 0, v82
	s_nop 1
	v_cndmask_b32_e64 v82, v83, v84, s[0:1]
	v_mul_f32_e32 v83, 0x37800000, v82
	v_cndmask_b32_e32 v82, v82, v83, vcc
	v_cmp_class_f32_e32 vcc, v81, v189
	s_nop 1
	v_cndmask_b32_e32 v81, v82, v81, vcc
	v_div_scale_f32 v82, s[0:1], v81, v81, 1.0
	v_rcp_f32_e32 v83, v82
	s_nop 0
	v_fma_f32 v84, -v82, v83, 1.0
	v_fmac_f32_e32 v83, v84, v83
	v_div_scale_f32 v84, vcc, 1.0, v81, 1.0
	v_mul_f32_e32 v85, v84, v83
	v_fma_f32 v86, -v82, v85, v84
	v_fmac_f32_e32 v85, v86, v83
	v_fma_f32 v82, -v82, v85, v84
	v_div_fmas_f32 v82, v82, v83, v85
	v_div_fixup_f32 v81, v82, v81, 1.0
	v_mul_f32_e32 v66, v66, v81
	v_mul_f32_e32 v68, v68, v81
	v_mul_f32_e32 v0, v0, v81
	v_mul_f32_e32 v67, v67, v81
	v_fma_f32 v65, v3, v68, v65
	v_fma_f32 v63, v5, v66, v63
	v_fma_f32 v64, v2, v67, v64
	v_fmac_f32_e32 v62, v4, v0
	v_mul_f32_e32 v0, v63, v63
	v_mul_f32_e32 v68, v65, v65
	v_fmac_f32_e32 v0, v62, v62
	v_fmac_f32_e32 v68, v64, v64
	v_add_f32_e32 v0, v0, v68
	v_mul_f32_e32 v68, v69, v81
	v_mul_f32_e32 v69, v70, v81
	v_mul_f32_e32 v70, v71, v81
	v_mul_f32_e32 v71, v72, v81
	v_fma_f32 v61, v15, v71, v61
	v_fma_f32 v59, v17, v69, v59
	v_fma_f32 v60, v14, v70, v60
	v_fmac_f32_e32 v58, v16, v68
	v_mul_f32_e32 v68, v59, v59
	v_mul_f32_e32 v69, v61, v61
	v_fmac_f32_e32 v68, v58, v58
	v_fmac_f32_e32 v69, v60, v60
	v_add_f32_e32 v68, v68, v69
	v_mul_f32_e32 v69, v74, v81
	v_mul_f32_e32 v71, v76, v81
	v_add_f32_e32 v0, v0, v68
	v_mul_f32_e32 v68, v73, v81
	v_mul_f32_e32 v70, v75, v81
	v_fma_f32 v57, v27, v71, v57
	v_fma_f32 v55, v29, v69, v55
	v_fma_f32 v56, v26, v70, v56
	v_fmac_f32_e32 v54, v28, v68
	v_mul_f32_e32 v68, v55, v55
	v_mul_f32_e32 v69, v57, v57
	v_fmac_f32_e32 v68, v54, v54
	v_fmac_f32_e32 v69, v56, v56
	v_add_f32_e32 v68, v68, v69
	v_add_f32_e32 v0, v68, v0
	v_mul_f32_e32 v68, v77, v81
	v_mul_f32_e32 v69, v78, v81
	v_mul_f32_e32 v70, v79, v81
	v_mul_f32_e32 v71, v80, v81
	v_lshl_add_u64 v[66:67], v[120:121], 0, v[126:127]
	v_fma_f32 v53, v39, v71, v53
	v_fma_f32 v52, v38, v70, v52
	v_fma_f32 v51, v41, v69, v51
	v_fmac_f32_e32 v50, v40, v68
	s_nop 1
	s_nop 1
	s_nop 1
	s_nop 1
	v_mul_f32_e32 v66, v51, v51
	v_mul_f32_e32 v67, v53, v53
	v_fmac_f32_e32 v66, v50, v50
	v_fmac_f32_e32 v67, v52, v52
	v_add_f32_e32 v66, v66, v67
	v_add_f32_e32 v0, v66, v0
	s_nop 1
	v_add_f32_dpp v0, v0, v0 quad_perm:[1,0,3,2] row_mask:0xf bank_mask:0xf bound_ctrl:1
	s_nop 1
	v_add_f32_dpp v0, v0, v0 quad_perm:[2,3,0,1] row_mask:0xf bank_mask:0xf bound_ctrl:1
	s_nop 1
	v_add_f32_dpp v0, v0, v0 row_half_mirror row_mask:0xf bank_mask:0xf bound_ctrl:1
	s_nop 1
	v_add_f32_dpp v0, v0, v0 row_mirror row_mask:0xf bank_mask:0xf bound_ctrl:1
	s_nop 0
	v_readlane_b32 s1, v0, 16
	v_readlane_b32 s6, v0, 48
	v_readlane_b32 s0, v0, 0
	v_readlane_b32 s2, v0, 32
	v_mov_b32_e32 v0, s1
	v_mov_b32_e32 v66, s6
	v_add_f32_e32 v0, s0, v0
	v_add_f32_e32 v66, s2, v66
	v_add_f32_e32 v0, v0, v66
	v_fmamk_f32 v0, v0, 0x3a800000, v188
	v_cmp_gt_f32_e32 vcc, s49, v0
	v_mul_f32_e32 v66, 0x4f800000, v0
	s_nop 0
	v_cndmask_b32_e32 v0, v0, v66, vcc
	v_sqrt_f32_e32 v66, v0
	s_nop 0
	v_add_u32_e32 v67, -1, v66
	v_fma_f32 v68, -v67, v66, v0
	v_cmp_ge_f32_e64 s[0:1], 0, v68
	v_add_u32_e32 v68, 1, v66
	s_nop 0
	v_cndmask_b32_e64 v67, v66, v67, s[0:1]
	v_fma_f32 v66, -v68, v66, v0
	v_cmp_lt_f32_e64 s[0:1], 0, v66
	s_nop 1
	v_cndmask_b32_e64 v66, v67, v68, s[0:1]
	v_mul_f32_e32 v67, 0x37800000, v66
	v_cndmask_b32_e32 v66, v66, v67, vcc
	v_cmp_class_f32_e32 vcc, v0, v189
	s_nop 1
	v_cndmask_b32_e32 v0, v66, v0, vcc
	v_div_scale_f32 v66, s[0:1], v0, v0, 1.0
	v_rcp_f32_e32 v67, v66
	s_nop 0
	v_fma_f32 v68, -v66, v67, 1.0
	v_fmac_f32_e32 v67, v68, v67
	v_div_scale_f32 v68, vcc, 1.0, v0, 1.0
	v_mul_f32_e32 v69, v68, v67
	v_fma_f32 v70, -v66, v69, v68
	v_fmac_f32_e32 v69, v70, v67
	v_fma_f32 v66, -v66, v69, v68
	v_div_fmas_f32 v66, v66, v67, v69
	v_div_fixup_f32 v0, v66, v0, 1.0
	v_mul_f32_e32 v63, v63, v0
	v_mul_f32_e32 v62, v62, v0
	v_mul_f32_e32 v59, v59, v0
	v_mul_f32_e32 v58, v58, v0
	v_mul_f32_e32 v55, v55, v0
	v_mul_f32_e32 v54, v54, v0
	v_mul_f32_e32 v51, v51, v0
	v_mul_f32_e32 v50, v50, v0
	v_cmp_lt_i32_e32 vcc, s61, v172
	v_lshl_add_u64 v[66:67], v[118:119], 0, v[124:125]
	v_mul_f32_e32 v65, v65, v0
	v_mul_f32_e32 v64, v64, v0
	v_fma_f32 v62, v8, v62, v10
	v_fma_f32 v63, v9, v63, v11
	v_mul_f32_e32 v61, v61, v0
	v_mul_f32_e32 v60, v60, v0
	v_fma_f32 v58, v20, v58, v22
	v_fma_f32 v59, v21, v59, v23
	v_mul_f32_e32 v57, v57, v0
	v_mul_f32_e32 v56, v56, v0
	v_fma_f32 v54, v32, v54, v34
	v_fma_f32 v55, v33, v55, v35
	v_mul_f32_e32 v53, v53, v0
	v_mul_f32_e32 v0, v52, v0
	v_fma_f32 v50, v44, v50, v46
	v_fma_f32 v51, v45, v51, v47
	s_or_b64 s[42:43], vcc, s[42:43]
	v_fma_f32 v64, v6, v64, v12
	v_fma_f32 v65, v7, v65, v13
	v_cvt_pk_bf16_f32 v62, v62, v63
	v_cvt_pk_bf16_f32 v63, v64, v65
	global_store_dwordx2 v[66:67], v[62:63], off
	v_fma_f32 v60, v18, v60, v24
	v_fma_f32 v61, v19, v61, v25
	v_cvt_pk_bf16_f32 v58, v58, v59
	v_cvt_pk_bf16_f32 v59, v60, v61
	global_store_dwordx2 v[66:67], v[58:59], off offset:512
	v_fma_f32 v56, v30, v56, v36
	v_fma_f32 v57, v31, v57, v37
	v_cvt_pk_bf16_f32 v54, v54, v55
	v_cvt_pk_bf16_f32 v55, v56, v57
	global_store_dwordx2 v[66:67], v[54:55], off offset:1024
	v_fma_f32 v0, v42, v0, v48
	v_fma_f32 v52, v43, v53, v49
	v_cvt_pk_bf16_f32 v50, v50, v51
	v_cvt_pk_bf16_f32 v51, v0, v52
	global_store_dwordx2 v[66:67], v[50:51], off offset:1536
	s_andn2_b64 exec, exec, s[42:43]
	s_cbranch_execnz .LBB0_33

.LBB0_36:
	s_andn2_b64 vcc, exec, s[0:1]
	s_cbranch_vccnz .LBB0_57
	v_readlane_b32 s0, v253, 33
	v_mov_b32_e32 v8, v186
	v_readlane_b32 s1, v253, 34
	s_andn2_b64 vcc, exec, s[0:1]
	v_readfirstlane_b32 s6, v8
	s_cbranch_vccnz .LBB0_57
	v_lshlrev_b32_e32 v0, 4, v8
	v_add_u32_e32 v3, 0x2000, v0
	v_ashrrev_i32_e32 v2, 31, v3
	v_lshrrev_b32_e32 v2, 22, v2
	v_add_u32_e32 v2, v3, v2
	v_ashrrev_i32_e32 v2, 10, v2
	v_mul_i32_i24_e32 v4, 0x400, v2
	v_sub_u32_e32 v3, v3, v4
	v_lshrrev_b32_e32 v4, 4, v3
	v_bitop3_b32 v4, v4, v3, 32 bitop3:0x6c
	v_ashrrev_i32_e32 v3, 31, v4
	v_lshrrev_b32_e32 v3, 26, v3
	v_add_u32_e32 v5, v4, v3
	v_lshlrev_b32_e32 v6, 3, v2
	v_readlane_b32 s66, v255, 8
	v_readlane_b32 s67, v255, 9
	s_cmp_eq_u32 s64, 0
	s_cselect_b32 s66, s66, s12
	s_cselect_b32 s67, s67, s13
	s_ashr_i32 s65, s64, 31
	v_ashrrev_i32_e32 v3, 6, v5
	v_and_b32_e32 v6, -16, v6
	s_lshl_b64 s[0:1], s[64:65], 22
	v_readlane_b32 s10, v253, 7
	v_add_u32_e32 v6, v3, v6
	s_add_u32 s2, s10, s0
	v_and_b32_e32 v7, 3, v3
	s_mov_b32 s0, 0xfffe0
	v_lshrrev_b32_e32 v9, 2, v6
	v_lshlrev_b32_e32 v10, 1, v6
	v_and_b32_e32 v5, 0xc0, v5
	v_and_or_b32 v7, v6, s0, v7
	v_and_b32_e32 v9, 4, v9
	v_and_b32_e32 v10, 24, v10
	v_sub_u32_e32 v4, v4, v5
	v_or3_b32 v7, v7, v9, v10
	v_lshlrev_b32_e32 v9, 5, v2
	v_ashrrev_i16_sdwa v4, v233, sext(v4) dst_sel:DWORD dst_unused:UNUSED_PAD src0_sel:DWORD src1_sel:BYTE_0
	v_and_b32_e32 v9, 32, v9
	v_bfe_i32 v4, v4, 0, 16
	v_add_lshl_u32 v5, v9, v4, 1
	v_lshl_add_u32 v130, v7, 12, v5
	v_lshl_add_u32 v132, v6, 12, v5
	v_bfe_i32 v5, v8, 27, 1
	v_lshrrev_b32_e32 v5, 22, v5
	v_add_u32_e32 v5, v0, v5
	v_and_b32_e32 v5, 0xfffffc00, v5
	v_sub_u32_e32 v0, v0, v5
	v_lshrrev_b32_e32 v5, 4, v0
	v_bitop3_b32 v7, v5, v0, 32 bitop3:0x6c
	v_ashrrev_i32_e32 v0, 31, v0
	v_lshrrev_b32_e32 v0, 26, v0
	v_add_u32_e32 v0, v7, v0
	v_ashrrev_i32_e32 v5, 6, v0
	v_ashrrev_i32_e32 v0, 31, v8
	v_lshrrev_b32_e32 v0, 26, v0
	v_add_u32_e32 v0, v8, v0
	v_ashrrev_i32_e32 v6, 6, v0
	v_lshlrev_b32_e32 v0, 3, v6
	v_and_b32_e32 v0, -16, v0
	v_add_u32_e32 v9, v5, v0
	v_and_b32_e32 v0, 3, v5
	v_lshrrev_b32_e32 v10, 2, v9
	v_lshlrev_b32_e32 v11, 1, v9
	v_and_or_b32 v0, v9, s0, v0
	v_and_b32_e32 v10, 4, v10
	v_and_b32_e32 v11, 24, v11
	v_readlane_b32 s11, v253, 8
	v_or3_b32 v0, v0, v10, v11
	v_mul_i32_i24_e32 v11, 64, v5
	s_addc_u32 s15, s11, s1
	s_ashr_i32 s7, s6, 6
	v_sub_u32_e32 v7, v7, v11
	s_ashr_i32 s10, s6, 8
	s_lshl_b32 s22, s7, 10
	v_lshlrev_b32_e32 v10, 5, v6
	v_ashrrev_i16_sdwa v7, v233, sext(v7) dst_sel:DWORD dst_unused:UNUSED_PAD src0_sel:DWORD src1_sel:BYTE_0
	v_readlane_b32 s0, v254, 59
	v_and_b32_e32 v10, 32, v10
	v_bfe_i32 v7, v7, 0, 16
	v_readlane_b32 s1, v254, 60
	s_add_u32 s44, s2, s0
	v_add_lshl_u32 v10, v10, v7, 1
	s_addc_u32 s45, s15, s1
	s_add_i32 s23, s22, 0
	v_lshl_add_u32 v0, v0, 12, v10
	s_add_i32 m0, s23, 0x10000
	v_lshl_add_u32 v134, v9, 12, v10
	global_load_lds_dwordx4 v0, s[44:45]
	s_add_i32 m0, s23, 0x12000
	s_add_u32 s0, s44, 0x80000
	global_load_lds_dwordx4 v130, s[44:45]
	s_addc_u32 s1, s45, 0
	s_add_i32 m0, s23, 0x14000
	s_add_i32 s41, s23, 0x2000
	global_load_lds_dwordx4 v0, s[0:1]
	s_add_i32 m0, s23, 0x16000
	s_add_i32 s40, s23, 0x4000
	global_load_lds_dwordx4 v130, s[0:1]
	v_readlane_b32 s0, v254, 63
	s_mov_b32 m0, s23
	v_readlane_b32 s1, v255, 0
	s_add_i32 s48, s23, 0x6000
	s_cmp_eq_u32 s10, 1
	s_nop 2
	global_load_lds_dwordx4 v134, s[0:1]
	s_mov_b32 m0, s41
	s_nop 0
	global_load_lds_dwordx4 v132, s[0:1]
	v_readlane_b32 s0, v255, 1
	s_mov_b32 m0, s40
	v_readlane_b32 s1, v255, 2
	s_nop 4
	global_load_lds_dwordx4 v134, s[0:1]
	s_mov_b32 m0, s48
	s_nop 0
	global_load_lds_dwordx4 v132, s[0:1]
	s_cselect_b64 s[0:1], -1, 0
	s_cmp_lg_u32 s10, 1
	s_cbranch_scc1 .LBB0_40
	s_barrier

.LBB0_53:
	v_lshl_add_u32 v146, s7, 8, v142
	v_lshl_or_b32 v140, s6, 8, v144
	v_ashrrev_i32_e32 v141, 31, v140
	v_ashrrev_i32_e32 v147, 31, v146
	v_lshl_add_u64 v[148:149], v[140:141], 1, s[66:67]
	v_lshlrev_b64 v[140:141], 11, v[146:147]
	v_lshl_add_u64 v[140:141], v[148:149], 0, v[140:141]
	v_add_f32_e32 v147, 0, v124
	v_add_f32_e32 v124, 0, v122
	v_cvt_pk_bf16_f32 v122, v126, v127
	v_add_f32_e32 v150, 0, v123
	v_cvt_pk_bf16_f32 v123, v128, v129
	v_cvt_pk_bf16_f32 v124, v124, v150
	v_cvt_pk_bf16_f32 v125, v147, v125
	global_store_dwordx4 v[140:141], v[122:125], off
	s_nop 1
	v_add_f32_e32 v122, 0, v108
	v_add_f32_e32 v108, 0, v106
	v_cvt_pk_bf16_f32 v106, v114, v115
	v_add_f32_e32 v123, 0, v107
	v_cvt_pk_bf16_f32 v107, v116, v117
	v_cvt_pk_bf16_f32 v108, v108, v123
	v_cvt_pk_bf16_f32 v109, v122, v109
	global_store_dwordx4 v[140:141], v[106:109], off offset:256
	s_nop 1
	v_or_b32_e32 v106, 16, v146
	v_ashrrev_i32_e32 v107, 31, v106
	v_lshlrev_b64 v[106:107], 11, v[106:107]
	v_lshl_add_u64 v[114:115], v[148:149], 0, v[106:107]
	v_add_f32_e32 v106, 0, v118
	v_add_f32_e32 v107, 0, v120
	v_add_f32_e32 v108, 0, v121
	v_add_f32_e32 v109, 0, v119
	v_cvt_pk_bf16_f32 v106, v106, v109
	v_cvt_pk_bf16_f32 v107, v107, v108
	v_cvt_pk_bf16_f32 v108, v110, v111
	v_cvt_pk_bf16_f32 v109, v112, v113
	global_store_dwordx4 v[114:115], v[106:109], off
	s_nop 1
	v_add_f32_e32 v106, 0, v92
	v_add_f32_e32 v92, 0, v90
	v_cvt_pk_bf16_f32 v90, v98, v99
	v_add_f32_e32 v107, 0, v91
	v_cvt_pk_bf16_f32 v91, v100, v101
	v_cvt_pk_bf16_f32 v92, v92, v107
	v_cvt_pk_bf16_f32 v93, v106, v93
	global_store_dwordx4 v[114:115], v[90:93], off offset:256
	s_nop 1
	v_or_b32_e32 v90, 32, v146
	v_ashrrev_i32_e32 v91, 31, v90
	v_lshlrev_b64 v[90:91], 11, v[90:91]
	v_lshl_add_u64 v[98:99], v[148:149], 0, v[90:91]
	v_add_f32_e32 v90, 0, v102
	v_add_f32_e32 v91, 0, v104
	v_add_f32_e32 v92, 0, v105
	v_add_f32_e32 v93, 0, v103
	v_cvt_pk_bf16_f32 v90, v90, v93
	v_cvt_pk_bf16_f32 v91, v91, v92
	v_cvt_pk_bf16_f32 v92, v94, v95
	v_cvt_pk_bf16_f32 v93, v96, v97
	global_store_dwordx4 v[98:99], v[90:93], off
	s_nop 1
	v_add_f32_e32 v90, 0, v76
	v_add_f32_e32 v76, 0, v74
	v_cvt_pk_bf16_f32 v74, v82, v83
	v_add_f32_e32 v91, 0, v75
	v_cvt_pk_bf16_f32 v75, v84, v85
	v_cvt_pk_bf16_f32 v76, v76, v91
	v_cvt_pk_bf16_f32 v77, v90, v77
	global_store_dwordx4 v[98:99], v[74:77], off offset:256
	s_nop 1
	v_or_b32_e32 v74, 48, v146
	v_ashrrev_i32_e32 v75, 31, v74
	v_lshlrev_b64 v[74:75], 11, v[74:75]
	v_lshl_add_u64 v[82:83], v[148:149], 0, v[74:75]
	v_add_f32_e32 v74, 0, v86
	v_add_f32_e32 v75, 0, v88
	v_add_f32_e32 v76, 0, v89
	v_add_f32_e32 v77, 0, v87
	v_cvt_pk_bf16_f32 v74, v74, v77
	v_cvt_pk_bf16_f32 v75, v75, v76
	v_cvt_pk_bf16_f32 v76, v78, v79
	v_cvt_pk_bf16_f32 v77, v80, v81
	global_store_dwordx4 v[82:83], v[74:77], off
	s_nop 1
	v_add_f32_e32 v74, 0, v68
	v_add_f32_e32 v68, 0, v66
	v_add_f32_e32 v75, 0, v67
	v_cvt_pk_bf16_f32 v66, v70, v71
	v_cvt_pk_bf16_f32 v67, v72, v73
	v_cvt_pk_bf16_f32 v68, v68, v75
	s_mov_b32 s6, 0x40000
	v_cvt_pk_bf16_f32 v69, v74, v69
	global_store_dwordx4 v[82:83], v[66:69], off offset:256
	s_nop 1
	v_add_f32_e32 v68, 0, v60
	v_add_f32_e32 v60, 0, v58
	v_cvt_pk_bf16_f32 v58, v62, v63
	v_add_co_u32_e32 v62, vcc, s6, v140
	s_nop 0
	v_addc_co_u32_e32 v63, vcc, 0, v141, vcc
	v_add_f32_e32 v69, 0, v59
	v_cvt_pk_bf16_f32 v59, v64, v65
	v_cvt_pk_bf16_f32 v60, v60, v69
	v_cvt_pk_bf16_f32 v61, v68, v61
	global_store_dwordx4 v[62:63], v[58:61], off
	s_nop 1
	v_lshl_add_u64 v[66:67], v[140:141], 0, s[36:37]
	v_add_f32_e32 v58, 0, v44
	v_add_f32_e32 v44, 0, v42
	v_add_f32_e32 v59, 0, v43
	v_cvt_pk_bf16_f32 v42, v50, v51
	v_cvt_pk_bf16_f32 v43, v52, v53
	v_cvt_pk_bf16_f32 v44, v44, v59
	s_mov_b64 s[6:7], 0x48000
	v_cvt_pk_bf16_f32 v45, v58, v45
	global_store_dwordx4 v[66:67], v[42:45], off offset:256
	s_nop 1
	v_lshl_add_u64 v[50:51], v[140:141], 0, s[6:7]
	v_add_f32_e32 v43, 0, v56
	v_add_f32_e32 v44, 0, v57
	v_add_f32_e32 v42, 0, v54
	s_mov_b32 s6, 0x48000
	v_add_f32_e32 v45, 0, v55
	v_cvt_pk_bf16_f32 v42, v42, v45
	v_cvt_pk_bf16_f32 v43, v43, v44
	v_cvt_pk_bf16_f32 v44, v46, v47
	v_add_co_u32_e32 v46, vcc, s6, v140
	s_nop 0
	v_addc_co_u32_e32 v47, vcc, 0, v141, vcc
	v_cvt_pk_bf16_f32 v45, v48, v49
	global_store_dwordx4 v[46:47], v[42:45], off
	s_nop 1
	v_add_f32_e32 v42, 0, v28
	v_add_f32_e32 v28, 0, v26
	v_add_f32_e32 v43, 0, v27
	v_cvt_pk_bf16_f32 v26, v34, v35
	v_cvt_pk_bf16_f32 v27, v36, v37
	v_cvt_pk_bf16_f32 v28, v28, v43
	s_mov_b64 s[6:7], 0x50000
	v_cvt_pk_bf16_f32 v29, v42, v29
	global_store_dwordx4 v[50:51], v[26:29], off offset:256
	s_nop 1
	v_lshl_add_u64 v[34:35], v[140:141], 0, s[6:7]
	v_add_f32_e32 v27, 0, v40
	v_add_f32_e32 v28, 0, v41
	v_add_f32_e32 v26, 0, v38
	s_mov_b32 s6, 0x50000
	v_add_f32_e32 v29, 0, v39
	v_cvt_pk_bf16_f32 v26, v26, v29
	v_cvt_pk_bf16_f32 v27, v27, v28
	v_cvt_pk_bf16_f32 v28, v30, v31
	v_add_co_u32_e32 v30, vcc, s6, v140
	s_nop 0
	v_addc_co_u32_e32 v31, vcc, 0, v141, vcc
	v_cvt_pk_bf16_f32 v29, v32, v33
	global_store_dwordx4 v[30:31], v[26:29], off
	s_nop 1
	v_add_f32_e32 v26, 0, v12
	v_add_f32_e32 v12, 0, v10
	v_add_f32_e32 v27, 0, v11
	v_cvt_pk_bf16_f32 v10, v18, v19
	v_cvt_pk_bf16_f32 v11, v20, v21
	v_cvt_pk_bf16_f32 v12, v12, v27
	s_mov_b64 s[6:7], 0x58000
	v_cvt_pk_bf16_f32 v13, v26, v13
	global_store_dwordx4 v[34:35], v[10:13], off offset:256
	s_nop 1
	v_lshl_add_u64 v[18:19], v[140:141], 0, s[6:7]
	v_add_f32_e32 v11, 0, v24
	v_add_f32_e32 v12, 0, v25
	v_add_f32_e32 v10, 0, v22
	s_mov_b32 s6, 0x58000
	v_add_f32_e32 v13, 0, v23
	v_cvt_pk_bf16_f32 v10, v10, v13
	v_cvt_pk_bf16_f32 v11, v11, v12
	v_cvt_pk_bf16_f32 v12, v14, v15
	v_add_co_u32_e32 v14, vcc, s6, v140
	s_nop 0
	v_addc_co_u32_e32 v15, vcc, 0, v141, vcc
	v_cvt_pk_bf16_f32 v13, v16, v17
	global_store_dwordx4 v[14:15], v[10:13], off
	s_nop 1
	s_andn2_b64 vcc, exec, s[38:39]
	v_add_f32_e32 v10, 0, v4
	v_add_f32_e32 v4, 0, v2
	s_mov_b64 s[10:11], -1
	v_add_f32_e32 v11, 0, v3
	v_cvt_pk_bf16_f32 v2, v6, v7
	v_cvt_pk_bf16_f32 v3, v8, v9
	v_cvt_pk_bf16_f32 v4, v4, v11
	v_cvt_pk_bf16_f32 v5, v10, v5
	global_store_dwordx4 v[18:19], v[2:5], off offset:256
	s_nop 1
	s_cbranch_vccnz .LBB0_42
	s_andn2_b64 vcc, exec, s[0:1]
	s_cbranch_vccnz .LBB0_41
	s_barrier
	s_branch .LBB0_41

.LBB0_58:
	s_andn2_b64 vcc, exec, s[0:1]
	s_cbranch_vccnz .LBB0_147
	s_cmp_eq_u32 s63, 1
	s_mov_b64 s[0:1], -1
	s_cbranch_scc1 .LBB0_81
	v_readlane_b32 s0, v253, 44
	v_mov_b32_e32 v2, v186
	v_readlane_b32 s1, v253, 45
	s_andn2_b64 vcc, exec, s[0:1]
	v_readfirstlane_b32 s6, v2
	s_cbranch_vccnz .LBB0_80
	v_lshlrev_b32_e32 v0, 4, v2
	v_add_u32_e32 v4, 0x2000, v0
	v_ashrrev_i32_e32 v3, 31, v4
	v_lshrrev_b32_e32 v3, 22, v3
	v_add_u32_e32 v3, v4, v3
	v_ashrrev_i32_e32 v3, 10, v3
	v_mul_i32_i24_e32 v5, 0x400, v3
	v_sub_u32_e32 v4, v4, v5
	v_lshrrev_b32_e32 v5, 4, v4
	v_bitop3_b32 v5, v5, v4, 32 bitop3:0x6c
	v_ashrrev_i32_e32 v4, 31, v5
	v_lshrrev_b32_e32 v4, 26, v4
	v_add_u32_e32 v6, v5, v4
	v_lshlrev_b32_e32 v7, 3, v3
	s_lshl_b32 s66, s64, 26
	s_ashr_i32 s65, s64, 31
	v_ashrrev_i32_e32 v4, 6, v6
	v_and_b32_e32 v7, -16, v7
	s_lshl_b64 s[0:1], s[64:65], 23
	v_add_u32_e32 v7, v4, v7
	s_add_u32 s2, s90, s0
	v_and_b32_e32 v8, 3, v4
	s_mov_b32 s0, 0x1fffe0
	v_lshrrev_b32_e32 v9, 2, v7
	v_lshlrev_b32_e32 v10, 1, v7
	v_and_b32_e32 v6, 0xc0, v6
	v_and_or_b32 v8, v7, s0, v8
	v_and_b32_e32 v9, 4, v9
	v_and_b32_e32 v10, 24, v10
	v_sub_u32_e32 v5, v5, v6
	v_or3_b32 v8, v8, v9, v10
	v_lshlrev_b32_e32 v9, 5, v3
	v_ashrrev_i16_sdwa v5, v233, sext(v5) dst_sel:DWORD dst_unused:UNUSED_PAD src0_sel:DWORD src1_sel:BYTE_0
	v_and_b32_e32 v9, 32, v9
	v_bfe_i32 v5, v5, 0, 16
	v_add_lshl_u32 v6, v9, v5, 1
	v_lshl_add_u32 v130, v8, 11, v6
	v_lshl_add_u32 v132, v7, 11, v6
	v_bfe_i32 v6, v2, 27, 1
	v_lshrrev_b32_e32 v6, 22, v6
	v_add_u32_e32 v6, v0, v6
	v_and_b32_e32 v6, 0xfffffc00, v6
	v_sub_u32_e32 v0, v0, v6
	v_lshrrev_b32_e32 v6, 4, v0
	v_bitop3_b32 v8, v6, v0, 32 bitop3:0x6c
	v_ashrrev_i32_e32 v0, 31, v0
	v_lshrrev_b32_e32 v0, 26, v0
	v_add_u32_e32 v0, v8, v0
	v_ashrrev_i32_e32 v6, 6, v0
	v_ashrrev_i32_e32 v0, 31, v2
	v_lshrrev_b32_e32 v0, 26, v0
	v_add_u32_e32 v0, v2, v0
	v_ashrrev_i32_e32 v7, 6, v0
	v_lshlrev_b32_e32 v0, 3, v7
	v_and_b32_e32 v0, -16, v0
	v_add_u32_e32 v9, v6, v0
	v_and_b32_e32 v0, 3, v6
	v_lshrrev_b32_e32 v10, 2, v9
	v_lshlrev_b32_e32 v11, 1, v9
	v_and_or_b32 v0, v9, s0, v0
	v_and_b32_e32 v10, 4, v10
	v_and_b32_e32 v11, 24, v11
	v_or3_b32 v0, v0, v10, v11
	v_mul_i32_i24_e32 v11, 64, v6
	s_addc_u32 s15, s91, s1
	s_ashr_i32 s10, s6, 6
	v_sub_u32_e32 v8, v8, v11
	s_ashr_i32 s7, s6, 8
	s_lshl_b32 s22, s10, 10
	v_lshlrev_b32_e32 v10, 5, v7
	v_ashrrev_i16_sdwa v8, v233, sext(v8) dst_sel:DWORD dst_unused:UNUSED_PAD src0_sel:DWORD src1_sel:BYTE_0
	v_readlane_b32 s0, v255, 4
	v_and_b32_e32 v10, 32, v10
	v_bfe_i32 v8, v8, 0, 16
	v_readlane_b32 s1, v255, 5
	s_add_u32 s26, s2, s0
	v_add_lshl_u32 v10, v10, v8, 1
	s_addc_u32 s27, s15, s1
	s_add_i32 s23, s22, 0
	v_lshl_add_u32 v0, v0, 11, v10
	s_add_i32 m0, s23, 0x10000
	v_lshl_add_u32 v134, v9, 11, v10
	global_load_lds_dwordx4 v0, s[26:27]
	s_add_i32 m0, s23, 0x12000
	s_add_u32 s0, s26, 0x40000
	global_load_lds_dwordx4 v130, s[26:27]
	s_addc_u32 s1, s27, 0
	s_add_i32 m0, s23, 0x14000
	s_add_i32 s40, s23, 0x2000
	global_load_lds_dwordx4 v0, s[0:1]
	s_add_i32 m0, s23, 0x16000
	s_add_i32 s41, s23, 0x4000
	global_load_lds_dwordx4 v130, s[0:1]
	v_readlane_b32 s0, v255, 10
	s_mov_b32 m0, s23
	v_readlane_b32 s1, v255, 11
	s_add_u32 s0, s0, s66
	s_addc_u32 s1, s1, 0
	s_add_i32 s48, s23, 0x6000
	s_cmp_eq_u32 s7, 1
	s_nop 2
	global_load_lds_dwordx4 v134, s[0:1]
	s_mov_b32 m0, s40
	s_nop 0
	global_load_lds_dwordx4 v132, s[0:1]
	v_readlane_b32 s0, v255, 12
	s_mov_b32 m0, s41
	v_readlane_b32 s1, v255, 13
	s_add_u32 s0, s0, s66
	s_addc_u32 s1, s1, 0
	s_nop 4
	global_load_lds_dwordx4 v134, s[0:1]
	s_mov_b32 m0, s48
	s_nop 0
	global_load_lds_dwordx4 v132, s[0:1]
	s_cmp_eq_u32 s7, 1
	s_cselect_b64 s[0:1], -1, 0
	s_cmp_lg_u32 s7, 1
	s_cbranch_scc1 .LBB0_63
	s_barrier
.LBB0_63:
	v_lshl_add_u64 v[10:11], s[26:27], 0, v[0:1]
	v_mov_b32_e32 v131, v1
	v_readlane_b32 s38, v255, 10
	s_lshl_b32 s10, s10, 5
	v_lshl_add_u64 v[12:13], s[26:27], 0, v[130:131]
	v_mov_b32_e32 v135, v1
	v_readlane_b32 s39, v255, 11
	s_add_u32 s38, s38, s66
	s_addc_u32 s39, s39, 0
	s_and_b32 s20, s10, 0x60
	s_add_i32 m0, s23, 0x18000
	v_lshl_add_u64 v[10:11], v[10:11], 0, s[46:47]
	v_lshl_add_u64 v[14:15], s[38:39], 0, v[134:135]
	v_mov_b32_e32 v133, v1
	s_lshl_b32 s18, s7, 13
	s_lshl_b32 s19, s20, 7
	s_waitcnt vmcnt(2)
	s_barrier
	global_load_lds_dwordx4 v[10:11], off
	v_lshl_add_u64 v[10:11], v[12:13], 0, s[46:47]
	s_add_i32 m0, s23, 0x1a000
	s_add_i32 s31, s23, 0x8000
	s_add_i32 s95, s23, 0xa000
	v_lshl_add_u64 v[16:17], s[38:39], 0, v[132:133]
	global_load_lds_dwordx4 v[10:11], off
	v_lshl_add_u64 v[10:11], v[14:15], 0, s[46:47]
	s_mov_b32 m0, s31
	s_add_u32 s10, s26, 0x40080
	global_load_lds_dwordx4 v[10:11], off
	v_lshl_add_u64 v[10:11], v[16:17], 0, s[46:47]
	s_mov_b32 m0, s95
	s_addc_u32 s11, s27, 0
	global_load_lds_dwordx4 v[10:11], off
	s_add_i32 m0, s23, 0x1c000
	v_lshl_add_u64 v[10:11], s[10:11], 0, v[0:1]
	global_load_lds_dwordx4 v[10:11], off
	v_lshl_add_u64 v[10:11], s[10:11], 0, v[130:131]
	s_add_i32 m0, s23, 0x1e000
	v_and_b32_e32 v9, 15, v2
	global_load_lds_dwordx4 v[10:11], off
	v_lshrrev_b32_e32 v10, 1, v2
	v_and_b32_e32 v10, 24, v10
	v_lshlrev_b32_e32 v11, 1, v10
	v_lshlrev_b32_e32 v2, 2, v2
	v_lshl_or_b32 v142, s7, 6, v9
	v_lshl_or_b32 v9, v9, 6, v11
	v_and_b32_e32 v2, 32, v2
	v_bitop3_b32 v11, v9, s18, v2 bitop3:0xde
	v_bitop3_b32 v143, v9, s19, v2 bitop3:0xde
	v_lshlrev_b32_e32 v2, 14, v7
	v_and_b32_e32 v2, 0xffff8000, v2
	v_lshl_add_u32 v2, v6, 11, v2
	v_and_b32_e32 v6, 1, v7
	v_lshl_or_b32 v2, v6, 6, v2
	v_lshl_add_u32 v136, v8, 1, v2
	v_lshlrev_b32_e32 v2, 14, v3
	v_and_b32_e32 v2, 0xffff8000, v2
	s_waitcnt vmcnt(6)
	v_lshl_add_u32 v2, v4, 11, v2
	v_and_b32_e32 v3, 1, v3
	v_readlane_b32 s10, v255, 6
	s_cmpk_lt_u32 s6, 0x100
	v_lshl_or_b32 v2, v3, 6, v2
	v_readlane_b32 s11, v255, 7
	s_cselect_b64 s[18:19], -1, 0
	v_or_b32_e32 v144, s20, v10
	v_mov_b32_e32 v137, v1
	v_lshl_add_u32 v138, v5, 1, v2
	v_mov_b32_e32 v139, v1
	s_mov_b32 s28, 0
	v_add_u32_e32 v145, 0, v11
	v_readlane_b32 s7, v255, 3
	s_mov_b32 s6, s10
	s_mov_b64 s[10:11], s[38:39]
	s_barrier
	s_branch .LBB0_66

.LBB0_72:
	s_ashr_i32 s35, s34, 31
	s_lshl_b64 s[42:43], s[34:35], 19
	v_readlane_b32 s44, v255, 8
	v_readlane_b32 s45, v255, 9
	s_add_u32 s44, s44, s66
	s_addc_u32 s45, s45, 0
	s_add_u32 s42, s44, s42
	s_addc_u32 s43, s45, s43
	s_and_b64 s[44:45], s[38:39], exec
	s_cselect_b32 s35, s43, s11
	s_cselect_b32 s52, s42, s10
	s_ashr_i32 s21, s20, 31
	s_lshl_b64 s[44:45], s[20:21], 19
	s_add_u32 s44, s2, s44
	s_addc_u32 s45, s15, s45
	s_and_b64 s[54:55], s[38:39], exec
	s_cselect_b32 s21, s45, s27
	s_cselect_b32 s53, s44, s26
	s_add_u32 vcc_lo, s10, 0x40080
	s_addc_u32 vcc_hi, s11, 0
	s_add_u32 s54, s26, 0x100
	s_addc_u32 s55, s27, 0
	s_mov_b32 s56, -2
	s_add_u32 s10, vcc_lo, 0xfffc0080
	s_addc_u32 s11, vcc_hi, -1
	s_add_i32 s57, 0, 0x10000
	s_cmp_eq_u32 s56, 12
	s_cselect_b32 s11, s35, s11
	s_cselect_b32 s10, s52, s10
	v_add_u32_e32 v140, s57, v143
	s_cselect_b32 s27, s21, s55
	s_cselect_b32 s26, s53, s54
	s_add_i32 s60, 0, 0x14000
	ds_read_b128 v[146:149], v140
	ds_read_b128 v[150:153], v140 offset:1024
	ds_read_b128 v[154:157], v140 offset:2048
	ds_read_b128 v[158:161], v140 offset:3072
	v_add_u32_e32 v140, s60, v143
	ds_read_b128 v[162:165], v140
	ds_read_b128 v[166:169], v140 offset:1024
	ds_read_b128 v[170:173], v140 offset:2048
	ds_read_b128 v[174:177], v140 offset:3072
	v_lshl_add_u64 v[140:141], vcc, 0, v[136:137]
	s_add_i32 m0, s23, 0xc000
	ds_read_b128 v[178:181], v145
	ds_read_b128 v[182:185], v145 offset:1024
	ds_read_b128 v[200:203], v145 offset:2048
	ds_read_b128 v[204:207], v145 offset:3072
	ds_read_b128 v[208:211], v145 offset:4096
	ds_read_b128 v[212:215], v145 offset:5120
	ds_read_b128 v[216:219], v145 offset:6144
	ds_read_b128 v[220:223], v145 offset:7168
	global_load_lds_dwordx4 v[140:141], off
	v_lshl_add_u64 v[140:141], vcc, 0, v[138:139]
	s_add_i32 m0, s23, 0xe000
	s_nop 0
	global_load_lds_dwordx4 v[140:141], off
	s_waitcnt vmcnt(8)
	s_waitcnt lgkmcnt(0)
	s_barrier
	s_setprio 1
	s_waitcnt lgkmcnt(0)
	v_mfma_f32_16x16x32_bf16 v[126:129], v[146:149], v[178:181], 0
	v_mfma_f32_16x16x32_bf16 v[122:125], v[154:157], v[178:181], 0
	v_mfma_f32_16x16x32_bf16 v[118:121], v[146:149], v[200:203], 0
	v_mfma_f32_16x16x32_bf16 v[110:113], v[154:157], v[200:203], 0
	v_mfma_f32_16x16x32_bf16 v[102:105], v[146:149], v[208:211], 0
	v_mfma_f32_16x16x32_bf16 v[94:97], v[154:157], v[208:211], 0
	v_mfma_f32_16x16x32_bf16 v[86:89], v[146:149], v[216:219], 0
	v_mfma_f32_16x16x32_bf16 v[78:81], v[154:157], v[216:219], 0
	v_mfma_f32_16x16x32_bf16 v[126:129], v[150:153], v[182:185], v[126:129]
	v_mfma_f32_16x16x32_bf16 v[122:125], v[158:161], v[182:185], v[122:125]
	v_mfma_f32_16x16x32_bf16 v[118:121], v[150:153], v[204:207], v[118:121]
	v_mfma_f32_16x16x32_bf16 v[110:113], v[158:161], v[204:207], v[110:113]
	v_mfma_f32_16x16x32_bf16 v[102:105], v[150:153], v[212:215], v[102:105]
	v_mfma_f32_16x16x32_bf16 v[94:97], v[158:161], v[212:215], v[94:97]
	v_mfma_f32_16x16x32_bf16 v[86:89], v[150:153], v[220:223], v[86:89]
	v_mfma_f32_16x16x32_bf16 v[78:81], v[158:161], v[220:223], v[78:81]
	s_setprio 0
	s_setprio 1
	v_mfma_f32_16x16x32_bf16 v[114:117], v[162:165], v[178:181], 0
	v_mfma_f32_16x16x32_bf16 v[106:109], v[170:173], v[178:181], 0
	v_mfma_f32_16x16x32_bf16 v[98:101], v[162:165], v[200:203], 0
	v_mfma_f32_16x16x32_bf16 v[90:93], v[170:173], v[200:203], 0
	v_mfma_f32_16x16x32_bf16 v[82:85], v[162:165], v[208:211], 0
	v_mfma_f32_16x16x32_bf16 v[74:77], v[170:173], v[208:211], 0
	v_mfma_f32_16x16x32_bf16 v[70:73], v[162:165], v[216:219], 0
	v_mfma_f32_16x16x32_bf16 v[66:69], v[170:173], v[216:219], 0
	v_mfma_f32_16x16x32_bf16 v[114:117], v[166:169], v[182:185], v[114:117]
	v_mfma_f32_16x16x32_bf16 v[106:109], v[174:177], v[182:185], v[106:109]
	v_mfma_f32_16x16x32_bf16 v[98:101], v[166:169], v[204:207], v[98:101]
	v_mfma_f32_16x16x32_bf16 v[90:93], v[174:177], v[204:207], v[90:93]
	v_mfma_f32_16x16x32_bf16 v[82:85], v[166:169], v[212:215], v[82:85]
	v_mfma_f32_16x16x32_bf16 v[74:77], v[174:177], v[212:215], v[74:77]
	v_mfma_f32_16x16x32_bf16 v[70:73], v[166:169], v[220:223], v[70:73]
	v_mfma_f32_16x16x32_bf16 v[66:69], v[174:177], v[220:223], v[66:69]
	s_setprio 0
	s_barrier
	s_add_i32 s57, s57, s22
	v_lshl_add_u64 v[140:141], s[26:27], 0, v[0:1]
	s_mov_b32 m0, s57
	ds_read_b128 v[178:181], v145 offset:16384
	ds_read_b128 v[182:185], v145 offset:17408
	ds_read_b128 v[200:203], v145 offset:18432
	ds_read_b128 v[204:207], v145 offset:19456
	ds_read_b128 v[208:211], v145 offset:20480
	ds_read_b128 v[212:215], v145 offset:21504
	ds_read_b128 v[216:219], v145 offset:22528
	ds_read_b128 v[220:223], v145 offset:23552
	global_load_lds_dwordx4 v[140:141], off
	s_add_i32 m0, s57, 0x2000
	s_add_u32 s58, s26, 0x40000
	v_lshl_add_u64 v[190:191], s[26:27], 0, v[130:131]
	s_addc_u32 s59, s27, 0
	s_add_i32 s57, s60, s22
	global_load_lds_dwordx4 v[190:191], off
	v_lshl_add_u64 v[192:193], s[58:59], 0, v[0:1]
	s_mov_b32 m0, s57
	v_lshl_add_u64 v[224:225], s[10:11], 0, v[132:133]
	global_load_lds_dwordx4 v[192:193], off
	v_lshl_add_u64 v[192:193], s[58:59], 0, v[130:131]
	s_add_i32 m0, s57, 0x2000
	s_nop 0
	global_load_lds_dwordx4 v[192:193], off
	v_lshl_add_u64 v[192:193], s[10:11], 0, v[134:135]
	s_mov_b32 m0, s23
	s_nop 0
	global_load_lds_dwordx4 v[192:193], off
	s_mov_b32 m0, s40
	s_nop 0
	global_load_lds_dwordx4 v[224:225], off
	s_waitcnt vmcnt(8)
	s_waitcnt lgkmcnt(0)
	s_barrier
	s_setprio 1
	s_waitcnt lgkmcnt(0)
	v_mfma_f32_16x16x32_bf16 v[62:65], v[146:149], v[178:181], 0
	v_mfma_f32_16x16x32_bf16 v[58:61], v[154:157], v[178:181], 0
	v_mfma_f32_16x16x32_bf16 v[54:57], v[146:149], v[200:203], 0
	v_mfma_f32_16x16x32_bf16 v[46:49], v[154:157], v[200:203], 0
	v_mfma_f32_16x16x32_bf16 v[38:41], v[146:149], v[208:211], 0
	v_mfma_f32_16x16x32_bf16 v[30:33], v[154:157], v[208:211], 0
	v_mfma_f32_16x16x32_bf16 v[22:25], v[146:149], v[216:219], 0
	v_mfma_f32_16x16x32_bf16 v[14:17], v[154:157], v[216:219], 0
	v_mfma_f32_16x16x32_bf16 v[62:65], v[150:153], v[182:185], v[62:65]
	v_mfma_f32_16x16x32_bf16 v[58:61], v[158:161], v[182:185], v[58:61]
	v_mfma_f32_16x16x32_bf16 v[54:57], v[150:153], v[204:207], v[54:57]
	v_mfma_f32_16x16x32_bf16 v[46:49], v[158:161], v[204:207], v[46:49]
	v_mfma_f32_16x16x32_bf16 v[38:41], v[150:153], v[212:215], v[38:41]
	v_mfma_f32_16x16x32_bf16 v[30:33], v[158:161], v[212:215], v[30:33]
	v_mfma_f32_16x16x32_bf16 v[22:25], v[150:153], v[220:223], v[22:25]
	v_mfma_f32_16x16x32_bf16 v[14:17], v[158:161], v[220:223], v[14:17]
	s_setprio 0
	s_setprio 1
	v_mfma_f32_16x16x32_bf16 v[50:53], v[162:165], v[178:181], 0
	v_mfma_f32_16x16x32_bf16 v[42:45], v[170:173], v[178:181], 0
	v_mfma_f32_16x16x32_bf16 v[34:37], v[162:165], v[200:203], 0
	v_mfma_f32_16x16x32_bf16 v[26:29], v[170:173], v[200:203], 0
	v_mfma_f32_16x16x32_bf16 v[18:21], v[162:165], v[208:211], 0
	v_mfma_f32_16x16x32_bf16 v[10:13], v[170:173], v[208:211], 0
	v_mfma_f32_16x16x32_bf16 v[6:9], v[162:165], v[216:219], 0
	v_mfma_f32_16x16x32_bf16 v[2:5], v[170:173], v[216:219], 0
	v_mfma_f32_16x16x32_bf16 v[50:53], v[166:169], v[182:185], v[50:53]
	v_mfma_f32_16x16x32_bf16 v[42:45], v[174:177], v[182:185], v[42:45]
	v_mfma_f32_16x16x32_bf16 v[34:37], v[166:169], v[204:207], v[34:37]
	v_mfma_f32_16x16x32_bf16 v[26:29], v[174:177], v[204:207], v[26:29]
	v_mfma_f32_16x16x32_bf16 v[18:21], v[166:169], v[212:215], v[18:21]
	v_mfma_f32_16x16x32_bf16 v[10:13], v[174:177], v[212:215], v[10:13]
	v_mfma_f32_16x16x32_bf16 v[6:9], v[166:169], v[220:223], v[6:9]
	v_mfma_f32_16x16x32_bf16 v[2:5], v[174:177], v[220:223], v[2:5]
	s_setprio 0
	s_barrier
	s_branch .Lg73_mid
